# v32 plus prep-phase rms-norm row sums via v_permlane16/32_swap instead of ds_bpermute
# baseline (speedup 1.0000x reference)
; DI f32x4 mfma16(bf16x8 a, bf16x8 b, f32x4 c) { return __builtin_amdgcn_mfma_f32_16x16x32_bf16(a, b, c, 0, 0, 0); }
; #define GLOAD0(kt) { GL(xa0, ag, lda, voa, 0, kt); GL(xa1, ag, lda, voa, 1, kt); GL(xa2, ag, lda, voa, 2, kt); GL(xa3, ag, lda, voa, 3, kt); GL(xb0, bg, ldb, vob, 0, kt); GL(xb1, bg, ldb, vob, 1, kt); GL(xb2, bg, ldb, vob, 2, kt); GL(xb3, bg, ldb, vob, 3, kt); }
; #define GLOAD1(kt) { GL(ya0, ag, lda, voa, 0, kt); GL(ya1, ag, lda, voa, 1, kt); GL(ya2, ag, lda, voa, 2, kt); GL(ya3, ag, lda, voa, 3, kt); GL(yb0, bg, ldb, vob, 0, kt); GL(yb1, bg, ldb, vob, 1, kt); GL(yb2, bg, ldb, vob, 2, kt); GL(yb3, bg, ldb, vob, 3, kt); }
; DI void gemm_block(f32x4 (&acc)[4][4], const u16* Ap, int lda, const u16* Bp, int ldb, int K, char* lds, int tid, bool swap_w1 = false) {
;     ...
;   auto compute = [&](int buf) {
; #pragma unroll
;     for (int ks = 0; ks < 2; ++ks) {
;       bf16x8 a[4], b[4];
; #pragma unroll
;       for (int i = 0; i < 4; ++i) a[i] = *reinterpret_cast<const bf16x8*>(a0p + buf * G_BUF_BYTES + i * 16 * GROW * 2 + ks * 64);
; #pragma unroll
;       for (int j = 0; j < 4; ++j) b[j] = *reinterpret_cast<const bf16x8*>(b0p + buf * G_BUF_BYTES + j * 16 * GROW * 2 + ks * 64);
;       __builtin_amdgcn_s_setprio(1);
; #pragma unroll
;       for (int i = 0; i < 4; ++i)
; #pragma unroll
;         for (int j = 0; j < 4; ++j) acc[i][j] = mfma16(a[i], b[j], acc[i][j]);
;       __builtin_amdgcn_s_setprio(0);
;     }
;   };
;   const int nkt = K >> 6;
;   GLOAD0(0);
;   GLOAD1(1);
;   GSTORE0(0);
;   __syncthreads();
;   for (int kt = 0; kt < nkt; kt += 2) {
;     if (kt + 2 < nkt) GLOAD0(kt + 2);
;     compute(0);
;     GSTORE1(1);
;     __syncthreads();
;     if (kt + 3 < nkt) GLOAD1(kt + 3);
;     compute(1);
;     if (kt + 2 < nkt) GSTORE0(0);
;     __syncthreads();
;   }
.LBB0_142:
	s_mov_b32 s31, s9
	s_lshl_b32 s0, s31, 7
	s_ashr_i32 s1, s0, 31
	s_lshl_b64 s[0:1], s[0:1], 9
	s_add_u32 s0, s88, s0
	s_addc_u32 s1, s89, s1
	v_lshl_add_u64 v[114:115], s[0:1], 0, v[48:49]
	v_add_co_u32_e32 v118, vcc, s63, v114
	global_load_dwordx4 v[0:3], v[114:115], off
	s_nop 0
	v_addc_co_u32_e32 v119, vcc, 0, v115, vcc
	v_add_co_u32_e32 v126, vcc, s80, v114
	global_load_dwordx4 v[4:7], v[118:119], off
	s_nop 0
	v_addc_co_u32_e32 v127, vcc, 0, v115, vcc
	global_load_dwordx4 v[8:11], v[126:127], off
	global_load_dwordx4 v[12:15], v[66:67], off offset:3408
	global_load_dwordx4 v[16:19], v[52:53], off
	global_load_dwordx4 v[20:23], v[54:55], off
	global_load_dwordx4 v[24:27], v[56:57], off
	s_mov_b32 s0, 0xc000
	v_add_co_u32_e32 v246, vcc, s0, v114
	v_readfirstlane_b32 s35, v138
	s_nop 0
	v_addc_co_u32_e32 v247, vcc, 0, v115, vcc
	global_load_dwordx4 v[28:31], v[246:247], off
	global_load_dwordx4 v[32:35], v[66:67], off offset:3536
	global_load_dwordx4 v[36:39], v[58:59], off
	global_load_dwordx4 v[40:43], v[60:61], off
	global_load_dwordx4 v[44:47], v[84:85], off
	global_load_dwordx4 v[100:103], v[114:115], off offset:128
	global_load_dwordx4 v[104:107], v[118:119], off offset:128
	global_load_dwordx4 v[108:111], v[126:127], off offset:128
	global_load_dwordx4 v[122:125], v[246:247], off offset:128
	s_lshr_b32 s0, s35, 1
	s_and_b32 s0, s0, 0xfffffc0
	v_or_b32_e32 v65, s0, v139
	v_mad_u64_u32 v[164:165], s[0:1], v65, s60, v[64:65]
	v_and_or_b32 v65, s35, 64, v139
	v_mad_u32_u24 v65, v65, s60, v64
	s_waitcnt vmcnt(12)
	ds_write_b128 v140, v[12:15] offset:18432
	s_waitcnt vmcnt(11)
	ds_write_b128 v140, v[16:19] offset:23040
	s_waitcnt vmcnt(10)
	ds_write_b128 v140, v[20:23] offset:27648
	s_waitcnt vmcnt(9)
	ds_write_b128 v140, v[24:27] offset:32256
	ds_write_b128 v140, v[0:3]
	ds_write_b128 v140, v[4:7] offset:4608
	ds_write_b128 v140, v[8:11] offset:9216
	s_waitcnt vmcnt(8)
	ds_write_b128 v140, v[28:31] offset:13824
	s_waitcnt lgkmcnt(0)
	s_barrier
	global_load_dwordx4 v[0:3], v[114:115], off offset:256
	global_load_dwordx4 v[4:7], v[118:119], off offset:256
	global_load_dwordx4 v[8:11], v[126:127], off offset:256
	global_load_dwordx4 v[12:15], v[246:247], off offset:256
	global_load_dwordx4 v[16:19], v[66:67], off offset:3664
	global_load_dwordx4 v[20:23], v[86:87], off
	global_load_dwordx4 v[24:27], v[88:89], off
	global_load_dwordx4 v[28:31], v[90:91], off
	ds_read_b128 v[134:137], v164
	ds_read_b128 v[146:149], v164 offset:2304
	ds_read_b128 v[150:153], v164 offset:4608
	ds_read_b128 v[154:157], v164 offset:6912
	ds_read_b128 v[158:161], v65 offset:18432
	ds_read_b128 v[170:173], v65 offset:20736
	ds_read_b128 v[174:177], v65 offset:23040
	ds_read_b128 v[178:181], v65 offset:25344
	s_setprio 1
	s_waitcnt lgkmcnt(3)
	v_mfma_f32_16x16x32_bf16 v[182:185], v[134:137], v[158:161], 0
	s_waitcnt lgkmcnt(2)
	v_mfma_f32_16x16x32_bf16 v[186:189], v[134:137], v[170:173], 0
	s_waitcnt lgkmcnt(1)
	v_mfma_f32_16x16x32_bf16 v[190:193], v[134:137], v[174:177], 0
	s_waitcnt lgkmcnt(0)
	v_mfma_f32_16x16x32_bf16 v[134:137], v[134:137], v[178:181], 0
	v_mfma_f32_16x16x32_bf16 v[194:197], v[146:149], v[158:161], 0
	v_mfma_f32_16x16x32_bf16 v[198:201], v[146:149], v[170:173], 0
	v_mfma_f32_16x16x32_bf16 v[202:205], v[146:149], v[174:177], 0
	v_mfma_f32_16x16x32_bf16 v[146:149], v[146:149], v[178:181], 0
	v_mfma_f32_16x16x32_bf16 v[206:209], v[150:153], v[158:161], 0
	v_mfma_f32_16x16x32_bf16 v[210:213], v[150:153], v[170:173], 0
	v_mfma_f32_16x16x32_bf16 v[214:217], v[150:153], v[174:177], 0
	v_mfma_f32_16x16x32_bf16 v[150:153], v[150:153], v[178:181], 0
	v_mfma_f32_16x16x32_bf16 v[158:161], v[154:157], v[158:161], 0
	v_mfma_f32_16x16x32_bf16 v[170:173], v[154:157], v[170:173], 0
	v_mfma_f32_16x16x32_bf16 v[174:177], v[154:157], v[174:177], 0
	v_mfma_f32_16x16x32_bf16 v[154:157], v[154:157], v[178:181], 0
	s_setprio 0
	ds_read_b128 v[178:181], v164 offset:64
	ds_read_b128 v[218:221], v164 offset:2368
	ds_read_b128 v[222:225], v164 offset:4672
	ds_read_b128 v[226:229], v164 offset:6976
	ds_read_b128 v[230:233], v65 offset:18496
	ds_read_b128 v[234:237], v65 offset:20800
	ds_read_b128 v[238:241], v65 offset:23104
	ds_read_b128 v[242:245], v65 offset:25408
	s_setprio 1
	s_waitcnt lgkmcnt(3)
	v_mfma_f32_16x16x32_bf16 v[182:185], v[178:181], v[230:233], v[182:185]
	s_waitcnt lgkmcnt(2)
	v_mfma_f32_16x16x32_bf16 v[186:189], v[178:181], v[234:237], v[186:189]
	s_waitcnt lgkmcnt(1)
	v_mfma_f32_16x16x32_bf16 v[190:193], v[178:181], v[238:241], v[190:193]
	s_waitcnt lgkmcnt(0)
	v_mfma_f32_16x16x32_bf16 v[134:137], v[178:181], v[242:245], v[134:137]
	v_mfma_f32_16x16x32_bf16 v[178:181], v[218:221], v[230:233], v[194:197]
	v_mfma_f32_16x16x32_bf16 v[194:197], v[218:221], v[234:237], v[198:201]
	v_mfma_f32_16x16x32_bf16 v[198:201], v[218:221], v[238:241], v[202:205]
	v_mfma_f32_16x16x32_bf16 v[146:149], v[218:221], v[242:245], v[146:149]
	v_mfma_f32_16x16x32_bf16 v[202:205], v[222:225], v[230:233], v[206:209]
	v_mfma_f32_16x16x32_bf16 v[206:209], v[222:225], v[234:237], v[210:213]
	v_mfma_f32_16x16x32_bf16 v[210:213], v[222:225], v[238:241], v[214:217]
	v_mfma_f32_16x16x32_bf16 v[150:153], v[222:225], v[242:245], v[150:153]
	v_mfma_f32_16x16x32_bf16 v[158:161], v[226:229], v[230:233], v[158:161]
	v_mfma_f32_16x16x32_bf16 v[170:173], v[226:229], v[234:237], v[170:173]
	v_mfma_f32_16x16x32_bf16 v[174:177], v[226:229], v[238:241], v[174:177]
	v_mfma_f32_16x16x32_bf16 v[154:157], v[226:229], v[242:245], v[154:157]
	s_setprio 0
	s_waitcnt vmcnt(11)
	ds_write_b128 v140, v[100:103] offset:36864
	s_waitcnt vmcnt(10)
	ds_write_b128 v140, v[104:107] offset:41472
	s_waitcnt vmcnt(9)
	ds_write_b128 v140, v[108:111] offset:46080
	s_waitcnt vmcnt(8)
	ds_write_b128 v140, v[122:125] offset:50688
	ds_write_b128 v140, v[32:35] offset:55296
	ds_write_b128 v140, v[36:39] offset:59904
	ds_write_b128 v140, v[40:43] offset:64512
	ds_write_b128 v141, v[44:47]
	s_waitcnt lgkmcnt(0)
	s_barrier
; DI f32x4 mfma16(bf16x8 a, bf16x8 b, f32x4 c) { return __builtin_amdgcn_mfma_f32_16x16x32_bf16(a, b, c, 0, 0, 0); }
; #define GLOAD0(kt) { GL(xa0, ag, lda, voa, 0, kt); GL(xa1, ag, lda, voa, 1, kt); GL(xa2, ag, lda, voa, 2, kt); GL(xa3, ag, lda, voa, 3, kt); GL(xb0, bg, ldb, vob, 0, kt); GL(xb1, bg, ldb, vob, 1, kt); GL(xb2, bg, ldb, vob, 2, kt); GL(xb3, bg, ldb, vob, 3, kt); }
; #define GLOAD1(kt) { GL(ya0, ag, lda, voa, 0, kt); GL(ya1, ag, lda, voa, 1, kt); GL(ya2, ag, lda, voa, 2, kt); GL(ya3, ag, lda, voa, 3, kt); GL(yb0, bg, ldb, vob, 0, kt); GL(yb1, bg, ldb, vob, 1, kt); GL(yb2, bg, ldb, vob, 2, kt); GL(yb3, bg, ldb, vob, 3, kt); }
; DI void gemm_block(f32x4 (&acc)[4][4], const u16* Ap, int lda, const u16* Bp, int ldb, int K, char* lds, int tid, bool swap_w1 = false) {
;     ...
;   auto compute = [&](int buf) {
; #pragma unroll
;     for (int ks = 0; ks < 2; ++ks) {
;       bf16x8 a[4], b[4];
; #pragma unroll
;       for (int i = 0; i < 4; ++i) a[i] = *reinterpret_cast<const bf16x8*>(a0p + buf * G_BUF_BYTES + i * 16 * GROW * 2 + ks * 64);
; #pragma unroll
;       for (int j = 0; j < 4; ++j) b[j] = *reinterpret_cast<const bf16x8*>(b0p + buf * G_BUF_BYTES + j * 16 * GROW * 2 + ks * 64);
;       __builtin_amdgcn_s_setprio(1);
; #pragma unroll
;       for (int i = 0; i < 4; ++i)
; #pragma unroll
;         for (int j = 0; j < 4; ++j) acc[i][j] = mfma16(a[i], b[j], acc[i][j]);
;       __builtin_amdgcn_s_setprio(0);
;     }
;   };
;   const int nkt = K >> 6;
;   GLOAD0(0);
;   GLOAD1(1);
;   GSTORE0(0);
;   __syncthreads();
;   for (int kt = 0; kt < nkt; kt += 2) {
;     if (kt + 2 < nkt) GLOAD0(kt + 2);
;     compute(0);
;     GSTORE1(1);
;     __syncthreads();
;     if (kt + 3 < nkt) GLOAD1(kt + 3);
;     compute(1);
;     if (kt + 2 < nkt) GSTORE0(0);
;     __syncthreads();
;   }
	global_load_dwordx4 v[32:35], v[114:115], off offset:384
	global_load_dwordx4 v[36:39], v[118:119], off offset:384
	global_load_dwordx4 v[40:43], v[126:127], off offset:384
	global_load_dwordx4 v[44:47], v[246:247], off offset:384
	global_load_dwordx4 v[100:103], v[66:67], off offset:3792
	global_load_dwordx4 v[104:107], v[92:93], off
	global_load_dwordx4 v[108:111], v[94:95], off
	global_load_dwordx4 v[122:125], v[96:97], off
	ds_read_b128 v[214:217], v164 offset:36864
	ds_read_b128 v[218:221], v164 offset:39168
	ds_read_b128 v[222:225], v164 offset:41472
	ds_read_b128 v[226:229], v164 offset:43776
	ds_read_b128 v[230:233], v65 offset:55296
	ds_read_b128 v[234:237], v65 offset:57600
	ds_read_b128 v[238:241], v65 offset:59904
	ds_read_b128 v[242:245], v65 offset:62208
	s_setprio 1
	s_waitcnt lgkmcnt(3)
	v_mfma_f32_16x16x32_bf16 v[182:185], v[214:217], v[230:233], v[182:185]
	s_waitcnt lgkmcnt(2)
	v_mfma_f32_16x16x32_bf16 v[186:189], v[214:217], v[234:237], v[186:189]
	s_waitcnt lgkmcnt(1)
	v_mfma_f32_16x16x32_bf16 v[190:193], v[214:217], v[238:241], v[190:193]
	s_waitcnt lgkmcnt(0)
	v_mfma_f32_16x16x32_bf16 v[134:137], v[214:217], v[242:245], v[134:137]
	v_mfma_f32_16x16x32_bf16 v[178:181], v[218:221], v[230:233], v[178:181]
	v_mfma_f32_16x16x32_bf16 v[194:197], v[218:221], v[234:237], v[194:197]
	v_mfma_f32_16x16x32_bf16 v[198:201], v[218:221], v[238:241], v[198:201]
	v_mfma_f32_16x16x32_bf16 v[146:149], v[218:221], v[242:245], v[146:149]
	v_mfma_f32_16x16x32_bf16 v[202:205], v[222:225], v[230:233], v[202:205]
	v_mfma_f32_16x16x32_bf16 v[206:209], v[222:225], v[234:237], v[206:209]
	v_mfma_f32_16x16x32_bf16 v[210:213], v[222:225], v[238:241], v[210:213]
	v_mfma_f32_16x16x32_bf16 v[150:153], v[222:225], v[242:245], v[150:153]
	v_mfma_f32_16x16x32_bf16 v[158:161], v[226:229], v[230:233], v[158:161]
	v_mfma_f32_16x16x32_bf16 v[170:173], v[226:229], v[234:237], v[170:173]
	v_mfma_f32_16x16x32_bf16 v[174:177], v[226:229], v[238:241], v[174:177]
	v_mfma_f32_16x16x32_bf16 v[154:157], v[226:229], v[242:245], v[154:157]
	s_setprio 0
	ds_read_b128 v[214:217], v164 offset:36928
	ds_read_b128 v[218:221], v164 offset:39232
	ds_read_b128 v[222:225], v164 offset:41536
	ds_read_b128 v[226:229], v164 offset:43840
	ds_read_b128 v[230:233], v65 offset:55360
	ds_read_b128 v[234:237], v65 offset:57664
	ds_read_b128 v[238:241], v65 offset:59968
	ds_read_b128 v[242:245], v65 offset:62272
	s_setprio 1
	s_waitcnt lgkmcnt(3)
	v_mfma_f32_16x16x32_bf16 v[182:185], v[214:217], v[230:233], v[182:185]
	s_waitcnt lgkmcnt(2)
	v_mfma_f32_16x16x32_bf16 v[186:189], v[214:217], v[234:237], v[186:189]
	s_waitcnt lgkmcnt(1)
	v_mfma_f32_16x16x32_bf16 v[190:193], v[214:217], v[238:241], v[190:193]
	s_waitcnt lgkmcnt(0)
	v_mfma_f32_16x16x32_bf16 v[134:137], v[214:217], v[242:245], v[134:137]
	v_mfma_f32_16x16x32_bf16 v[178:181], v[218:221], v[230:233], v[178:181]
	v_mfma_f32_16x16x32_bf16 v[194:197], v[218:221], v[234:237], v[194:197]
	v_mfma_f32_16x16x32_bf16 v[198:201], v[218:221], v[238:241], v[198:201]
	v_mfma_f32_16x16x32_bf16 v[146:149], v[218:221], v[242:245], v[146:149]
	v_mfma_f32_16x16x32_bf16 v[202:205], v[222:225], v[230:233], v[202:205]
	v_mfma_f32_16x16x32_bf16 v[206:209], v[222:225], v[234:237], v[206:209]
	v_mfma_f32_16x16x32_bf16 v[210:213], v[222:225], v[238:241], v[210:213]
	v_mfma_f32_16x16x32_bf16 v[150:153], v[222:225], v[242:245], v[150:153]
	v_mfma_f32_16x16x32_bf16 v[158:161], v[226:229], v[230:233], v[158:161]
	v_mfma_f32_16x16x32_bf16 v[170:173], v[226:229], v[234:237], v[170:173]
	v_mfma_f32_16x16x32_bf16 v[174:177], v[226:229], v[238:241], v[174:177]
	v_mfma_f32_16x16x32_bf16 v[154:157], v[226:229], v[242:245], v[154:157]
	s_setprio 0
	s_waitcnt vmcnt(15)
	ds_write_b128 v140, v[0:3]
	s_waitcnt vmcnt(14)
	ds_write_b128 v140, v[4:7] offset:4608
	s_waitcnt vmcnt(13)
	ds_write_b128 v140, v[8:11] offset:9216
	s_waitcnt vmcnt(12)
	ds_write_b128 v140, v[12:15] offset:13824
	s_waitcnt vmcnt(11)
	ds_write_b128 v140, v[16:19] offset:18432
	s_waitcnt vmcnt(10)
	ds_write_b128 v140, v[20:23] offset:23040
	s_waitcnt vmcnt(9)
	ds_write_b128 v140, v[24:27] offset:27648
	s_waitcnt vmcnt(8)
	ds_write_b128 v140, v[28:31] offset:32256
	s_waitcnt lgkmcnt(0)
	s_barrier
	ds_read_b128 v[0:3], v164
	ds_read_b128 v[4:7], v164 offset:2304
	ds_read_b128 v[8:11], v164 offset:4608
	ds_read_b128 v[12:15], v164 offset:6912
	ds_read_b128 v[16:19], v65 offset:18432
	ds_read_b128 v[20:23], v65 offset:20736
	ds_read_b128 v[24:27], v65 offset:23040
	ds_read_b128 v[28:31], v65 offset:25344
	s_setprio 1
	s_waitcnt lgkmcnt(3)
	v_mfma_f32_16x16x32_bf16 v[182:185], v[0:3], v[16:19], v[182:185]
	s_waitcnt lgkmcnt(2)
	v_mfma_f32_16x16x32_bf16 v[186:189], v[0:3], v[20:23], v[186:189]
	s_waitcnt lgkmcnt(1)
	v_mfma_f32_16x16x32_bf16 v[190:193], v[0:3], v[24:27], v[190:193]
	s_waitcnt lgkmcnt(0)
	v_mfma_f32_16x16x32_bf16 v[0:3], v[0:3], v[28:31], v[134:137]
	v_mfma_f32_16x16x32_bf16 v[134:137], v[4:7], v[16:19], v[178:181]
	v_mfma_f32_16x16x32_bf16 v[178:181], v[4:7], v[20:23], v[194:197]
	v_mfma_f32_16x16x32_bf16 v[194:197], v[4:7], v[24:27], v[198:201]
	v_mfma_f32_16x16x32_bf16 v[4:7], v[4:7], v[28:31], v[146:149]
	v_mfma_f32_16x16x32_bf16 v[146:149], v[8:11], v[16:19], v[202:205]
	v_mfma_f32_16x16x32_bf16 v[198:201], v[8:11], v[20:23], v[206:209]
	v_mfma_f32_16x16x32_bf16 v[202:205], v[8:11], v[24:27], v[210:213]
	v_mfma_f32_16x16x32_bf16 v[8:11], v[8:11], v[28:31], v[150:153]
	v_mfma_f32_16x16x32_bf16 v[16:19], v[12:15], v[16:19], v[158:161]
	v_mfma_f32_16x16x32_bf16 v[20:23], v[12:15], v[20:23], v[170:173]
	v_mfma_f32_16x16x32_bf16 v[24:27], v[12:15], v[24:27], v[174:177]
	v_mfma_f32_16x16x32_bf16 v[12:15], v[12:15], v[28:31], v[154:157]
	s_setprio 0
	ds_read_b128 v[28:31], v164 offset:64
	ds_read_b128 v[150:153], v164 offset:2368
	ds_read_b128 v[154:157], v164 offset:4672
	ds_read_b128 v[158:161], v164 offset:6976
	ds_read_b128 v[170:173], v65 offset:18496
	ds_read_b128 v[174:177], v65 offset:20800
	ds_read_b128 v[206:209], v65 offset:23104
	ds_read_b128 v[210:213], v65 offset:25408
	s_setprio 1
	s_waitcnt lgkmcnt(3)
; DI f32x4 mfma16(bf16x8 a, bf16x8 b, f32x4 c) { return __builtin_amdgcn_mfma_f32_16x16x32_bf16(a, b, c, 0, 0, 0); }
; DI float red4(float v) { v += __shfl_xor(v, 16); v += __shfl_xor(v, 32); return v; }
; #define GLOAD0(kt) { GL(xa0, ag, lda, voa, 0, kt); GL(xa1, ag, lda, voa, 1, kt); GL(xa2, ag, lda, voa, 2, kt); GL(xa3, ag, lda, voa, 3, kt); GL(xb0, bg, ldb, vob, 0, kt); GL(xb1, bg, ldb, vob, 1, kt); GL(xb2, bg, ldb, vob, 2, kt); GL(xb3, bg, ldb, vob, 3, kt); }
; #define GLOAD1(kt) { GL(ya0, ag, lda, voa, 0, kt); GL(ya1, ag, lda, voa, 1, kt); GL(ya2, ag, lda, voa, 2, kt); GL(ya3, ag, lda, voa, 3, kt); GL(yb0, bg, ldb, vob, 0, kt); GL(yb1, bg, ldb, vob, 1, kt); GL(yb2, bg, ldb, vob, 2, kt); GL(yb3, bg, ldb, vob, 3, kt); }
; DI void gemm_block(f32x4 (&acc)[4][4], const u16* Ap, int lda, const u16* Bp, int ldb, int K, char* lds, int tid, bool swap_w1 = false) {
;     ...
;   auto compute = [&](int buf) {
; #pragma unroll
;     for (int ks = 0; ks < 2; ++ks) {
;       bf16x8 a[4], b[4];
; #pragma unroll
;       for (int i = 0; i < 4; ++i) a[i] = *reinterpret_cast<const bf16x8*>(a0p + buf * G_BUF_BYTES + i * 16 * GROW * 2 + ks * 64);
; #pragma unroll
;       for (int j = 0; j < 4; ++j) b[j] = *reinterpret_cast<const bf16x8*>(b0p + buf * G_BUF_BYTES + j * 16 * GROW * 2 + ks * 64);
;       __builtin_amdgcn_s_setprio(1);
; #pragma unroll
;       for (int i = 0; i < 4; ++i)
; #pragma unroll
;         for (int j = 0; j < 4; ++j) acc[i][j] = mfma16(a[i], b[j], acc[i][j]);
;       __builtin_amdgcn_s_setprio(0);
;     }
;   };
;   const int nkt = K >> 6;
;   GLOAD0(0);
;   GLOAD1(1);
;   GSTORE0(0);
;   __syncthreads();
;   for (int kt = 0; kt < nkt; kt += 2) {
;     if (kt + 2 < nkt) GLOAD0(kt + 2);
;     compute(0);
;     GSTORE1(1);
;     __syncthreads();
;     if (kt + 3 < nkt) GLOAD1(kt + 3);
;     compute(1);
;     if (kt + 2 < nkt) GSTORE0(0);
;     __syncthreads();
; DI void prep_mla_tile(const Params& P, int l, int tt, char* lds, float* s_r, float* s_ss) {
;     ...
; #pragma unroll
;     for (int j = 0; j < 4; ++j) {
;       const int tl = wb * 64 + 16 * j + jn; const float rq = s_r[tl];
;       float ss = 0.f;
; #pragma unroll
;       for (int i = 0; i < 4; ++i)
; #pragma unroll
;         for (int r = 0; r < 4; ++r) { const float v = acc[i][j][r] * rq; acc[i][j][r] = v; ss += v * v; }
;       ss = red4(ss);
;       if (q == 0) s_ss[wa * 128 + tl] = ss;
;     }
	v_mfma_f32_16x16x32_bf16 v[182:185], v[28:31], v[170:173], v[182:185]
	s_waitcnt lgkmcnt(2)
	v_mfma_f32_16x16x32_bf16 v[186:189], v[28:31], v[174:177], v[186:189]
	s_waitcnt lgkmcnt(1)
	v_mfma_f32_16x16x32_bf16 v[190:193], v[28:31], v[206:209], v[190:193]
	s_waitcnt lgkmcnt(0)
	v_mfma_f32_16x16x32_bf16 v[0:3], v[28:31], v[210:213], v[0:3]
	v_mfma_f32_16x16x32_bf16 v[28:31], v[150:153], v[170:173], v[134:137]
	v_mfma_f32_16x16x32_bf16 v[4:7], v[150:153], v[210:213], v[4:7]
	v_mfma_f32_16x16x32_bf16 v[8:11], v[154:157], v[210:213], v[8:11]
	v_mfma_f32_16x16x32_bf16 v[16:19], v[158:161], v[170:173], v[16:19]
	v_mfma_f32_16x16x32_bf16 v[20:23], v[158:161], v[174:177], v[20:23]
	v_mfma_f32_16x16x32_bf16 v[24:27], v[158:161], v[206:209], v[24:27]
	v_mfma_f32_16x16x32_bf16 v[12:15], v[158:161], v[210:213], v[12:15]
	v_mfma_f32_16x16x32_bf16 v[134:137], v[150:153], v[174:177], v[178:181]
	v_mfma_f32_16x16x32_bf16 v[178:181], v[150:153], v[206:209], v[194:197]
	v_mfma_f32_16x16x32_bf16 v[146:149], v[154:157], v[170:173], v[146:149]
	v_mfma_f32_16x16x32_bf16 v[150:153], v[154:157], v[174:177], v[198:201]
	v_mfma_f32_16x16x32_bf16 v[194:197], v[154:157], v[206:209], v[202:205]
	s_setprio 0
	s_waitcnt vmcnt(7)
	ds_write_b128 v140, v[32:35] offset:36864
	s_waitcnt vmcnt(6)
	ds_write_b128 v140, v[36:39] offset:41472
	s_waitcnt vmcnt(5)
	ds_write_b128 v140, v[40:43] offset:46080
	s_waitcnt vmcnt(4)
	ds_write_b128 v140, v[44:47] offset:50688
	s_waitcnt vmcnt(3)
	ds_write_b128 v140, v[100:103] offset:55296
	s_waitcnt vmcnt(2)
	ds_write_b128 v140, v[104:107] offset:59904
	s_waitcnt vmcnt(1)
	ds_write_b128 v140, v[108:111] offset:64512
	s_waitcnt vmcnt(0)
	ds_write_b128 v141, v[122:125]
	s_waitcnt lgkmcnt(0)
	s_barrier
	ds_read_b128 v[32:35], v164 offset:36864
	ds_read_b128 v[36:39], v164 offset:39168
	ds_read_b128 v[40:43], v164 offset:41472
	ds_read_b128 v[44:47], v164 offset:43776
	ds_read_b128 v[100:103], v65 offset:55296
	ds_read_b128 v[104:107], v65 offset:57600
	ds_read_b128 v[108:111], v65 offset:59904
	ds_read_b128 v[122:125], v65 offset:62208
	s_setprio 1
	s_waitcnt lgkmcnt(3)
	v_mfma_f32_16x16x32_bf16 v[154:157], v[32:35], v[100:103], v[182:185]
	s_waitcnt lgkmcnt(2)
	v_mfma_f32_16x16x32_bf16 v[158:161], v[32:35], v[104:107], v[186:189]
	s_waitcnt lgkmcnt(1)
	v_mfma_f32_16x16x32_bf16 v[170:173], v[32:35], v[108:111], v[190:193]
	s_waitcnt lgkmcnt(0)
	v_mfma_f32_16x16x32_bf16 v[0:3], v[32:35], v[122:125], v[0:3]
	v_mfma_f32_16x16x32_bf16 v[28:31], v[36:39], v[100:103], v[28:31]
	v_mfma_f32_16x16x32_bf16 v[32:35], v[36:39], v[104:107], v[134:137]
	v_mfma_f32_16x16x32_bf16 v[134:137], v[36:39], v[108:111], v[178:181]
	v_mfma_f32_16x16x32_bf16 v[4:7], v[36:39], v[122:125], v[4:7]
	v_mfma_f32_16x16x32_bf16 v[36:39], v[40:43], v[100:103], v[146:149]
	v_mfma_f32_16x16x32_bf16 v[146:149], v[40:43], v[104:107], v[150:153]
	v_mfma_f32_16x16x32_bf16 v[150:153], v[40:43], v[108:111], v[194:197]
	v_mfma_f32_16x16x32_bf16 v[16:19], v[44:47], v[100:103], v[16:19]
	v_mfma_f32_16x16x32_bf16 v[100:103], v[44:47], v[104:107], v[20:23]
	v_mfma_f32_16x16x32_bf16 v[104:107], v[44:47], v[108:111], v[24:27]
	v_mfma_f32_16x16x32_bf16 v[108:111], v[44:47], v[122:125], v[12:15]
	v_mfma_f32_16x16x32_bf16 v[174:177], v[40:43], v[122:125], v[8:11]
	s_setprio 0
	s_nop 1
	ds_read_b128 v[8:11], v164 offset:36928
	ds_read_b128 v[12:15], v164 offset:39232
	ds_read_b128 v[122:125], v164 offset:41536
	ds_read_b128 v[178:181], v164 offset:43840
	ds_read_b128 v[182:185], v65 offset:55360
	ds_read_b128 v[186:189], v65 offset:57664
	ds_read_b128 v[190:193], v65 offset:59968
	ds_read_b128 v[194:197], v65 offset:62272
	s_setprio 1
	s_waitcnt lgkmcnt(3)
	v_mfma_f32_16x16x32_bf16 v[154:157], v[8:11], v[182:185], v[154:157]
	s_waitcnt lgkmcnt(2)
	v_mfma_f32_16x16x32_bf16 v[40:43], v[8:11], v[186:189], v[158:161]
	s_waitcnt lgkmcnt(1)
	v_mfma_f32_16x16x32_bf16 v[24:27], v[8:11], v[190:193], v[170:173]
	s_waitcnt lgkmcnt(0)
	v_mfma_f32_16x16x32_bf16 v[8:11], v[8:11], v[194:197], v[0:3]
	v_mfma_f32_16x16x32_bf16 v[158:161], v[12:15], v[182:185], v[28:31]
	v_mfma_f32_16x16x32_bf16 v[44:47], v[12:15], v[186:189], v[32:35]
	v_mfma_f32_16x16x32_bf16 v[28:31], v[12:15], v[190:193], v[134:137]
	v_mfma_f32_16x16x32_bf16 v[12:15], v[12:15], v[194:197], v[4:7]
	v_mfma_f32_16x16x32_bf16 v[134:137], v[122:125], v[182:185], v[36:39]
	v_mfma_f32_16x16x32_bf16 v[36:39], v[122:125], v[186:189], v[146:149]
	v_mfma_f32_16x16x32_bf16 v[20:23], v[122:125], v[190:193], v[150:153]
	v_mfma_f32_16x16x32_bf16 v[4:7], v[122:125], v[194:197], v[174:177]
	v_mfma_f32_16x16x32_bf16 v[146:149], v[178:181], v[182:185], v[16:19]
	v_mfma_f32_16x16x32_bf16 v[32:35], v[178:181], v[186:189], v[100:103]
	v_mfma_f32_16x16x32_bf16 v[16:19], v[178:181], v[190:193], v[104:107]
	v_mfma_f32_16x16x32_bf16 v[0:3], v[178:181], v[194:197], v[108:111]
	s_setprio 0
	s_barrier
	ds_read_b32 v100, v144
	s_waitcnt lgkmcnt(0)
	v_mul_f32_e32 v115, v155, v100
	v_mul_f32_e32 v125, v154, v100
	v_mul_f32_e32 v65, v115, v115
	v_mul_f32_e32 v124, v156, v100
	v_mov_b32_e32 v156, v161
	v_fmac_f32_e32 v65, v125, v125
	v_pk_mul_f32 v[118:119], v[156:157], v[100:101] op_sel_hi:[1,0]
	v_fmac_f32_e32 v65, v124, v124
	v_pk_mul_f32 v[122:123], v[158:159], v[100:101] op_sel_hi:[1,0]
	v_pk_mul_f32 v[104:105], v[118:119], v[118:119]
	v_pk_mul_f32 v[102:103], v[122:123], v[122:123]
	v_add_f32_e32 v65, v105, v65
	v_add_f32_e32 v65, v102, v65
	v_mul_f32_e32 v114, v160, v100
	v_add_f32_e32 v65, v103, v65
	v_fmac_f32_e32 v65, v114, v114
	v_pk_mul_f32 v[110:111], v[134:135], v[100:101] op_sel_hi:[1,0]
	v_add_f32_e32 v65, v104, v65
	v_pk_mul_f32 v[102:103], v[110:111], v[110:111]
	v_pk_mul_f32 v[108:109], v[136:137], v[100:101] op_sel_hi:[1,0]
	v_add_f32_e32 v65, v102, v65
	v_add_f32_e32 v65, v103, v65
	v_pk_mul_f32 v[102:103], v[108:109], v[108:109]
	v_pk_mul_f32 v[106:107], v[146:147], v[100:101] op_sel_hi:[1,0]
	v_add_f32_e32 v65, v102, v65
	v_add_f32_e32 v65, v103, v65
	v_pk_mul_f32 v[102:103], v[106:107], v[106:107]
	v_pk_mul_f32 v[104:105], v[148:149], v[100:101] op_sel_hi:[1,0]
	v_add_f32_e32 v65, v102, v65
	v_add_f32_e32 v65, v103, v65
	v_pk_mul_f32 v[100:101], v[104:105], v[104:105]
	s_nop 0
	v_add_f32_e32 v65, v100, v65
	v_add_f32_e32 v65, v101, v65
	v_mov_b32_e32 v100, v65
	s_nop 1
	v_permlane16_swap_b32_e32 v100, v65
	s_waitcnt lgkmcnt(0)
	v_add_f32_e32 v65, v65, v100
	v_mov_b32_e32 v100, v65
	s_nop 1
	v_permlane32_swap_b32_e32 v100, v65
	s_and_saveexec_b64 s[0:1], s[2:3]
	s_cbranch_execz .LBB0_144
	s_waitcnt lgkmcnt(0)
	v_add_f32_e32 v65, v65, v100
	ds_write_b32 v113, v65 offset:1024
; DI float red4(float v) { v += __shfl_xor(v, 16); v += __shfl_xor(v, 32); return v; }
; DI void prep_mla_tile(const Params& P, int l, int tt, char* lds, float* s_r, float* s_ss) {
;     ...
; #pragma unroll
;     for (int j = 0; j < 4; ++j) {
;       const int tl = wb * 64 + 16 * j + jn; const float rq = s_r[tl];
;       float ss = 0.f;
; #pragma unroll
;       for (int i = 0; i < 4; ++i)
; #pragma unroll
;         for (int r = 0; r < 4; ++r) { const float v = acc[i][j][r] * rq; acc[i][j][r] = v; ss += v * v; }
;       ss = red4(ss);
;       if (q == 0) s_ss[wa * 128 + tl] = ss;
;     }
.LBB0_144:
	s_or_b64 exec, exec, s[0:1]
	ds_read_b32 v126, v144 offset:64
	s_waitcnt lgkmcnt(0)
	v_mul_f32_e32 v103, v41, v126
	v_mul_f32_e32 v121, v40, v126
	v_mul_f32_e32 v102, v42, v126
	v_pk_mul_f32 v[100:101], v[44:45], v[126:127] op_sel_hi:[1,0]
	v_mul_f32_e32 v45, v103, v103
	v_mov_b32_e32 v42, v47
	v_fmac_f32_e32 v45, v121, v121
	v_mul_f32_e32 v44, v46, v126
	v_pk_mul_f32 v[46:47], v[42:43], v[126:127] op_sel_hi:[1,0]
	v_fmac_f32_e32 v45, v102, v102
	v_pk_mul_f32 v[42:43], v[46:47], v[46:47]
	v_pk_mul_f32 v[40:41], v[100:101], v[100:101]
	v_add_f32_e32 v43, v43, v45
	v_add_f32_e32 v40, v40, v43
	v_add_f32_e32 v40, v41, v40
	v_fmac_f32_e32 v40, v44, v44
	v_add_f32_e32 v40, v42, v40
	v_pk_mul_f32 v[42:43], v[36:37], v[126:127] op_sel_hi:[1,0]
	s_nop 0
	v_pk_mul_f32 v[36:37], v[42:43], v[42:43]
	s_nop 0
	v_add_f32_e32 v36, v36, v40
	v_pk_mul_f32 v[40:41], v[38:39], v[126:127] op_sel_hi:[1,0]
	v_add_f32_e32 v45, v37, v36
	v_pk_mul_f32 v[36:37], v[40:41], v[40:41]
	v_pk_mul_f32 v[38:39], v[32:33], v[126:127] op_sel_hi:[1,0]
	v_add_f32_e32 v36, v36, v45
	v_add_f32_e32 v36, v37, v36
	v_pk_mul_f32 v[32:33], v[38:39], v[38:39]
	s_nop 0
	v_add_f32_e32 v32, v32, v36
	v_pk_mul_f32 v[36:37], v[34:35], v[126:127] op_sel_hi:[1,0]
	v_add_f32_e32 v45, v33, v32
	v_pk_mul_f32 v[32:33], v[36:37], v[36:37]
	s_nop 0
	v_add_f32_e32 v32, v32, v45
	v_add_f32_e32 v32, v33, v32
	v_mov_b32_e32 v33, v32
	s_nop 1
	v_permlane16_swap_b32_e32 v33, v32
	s_waitcnt lgkmcnt(0)
	v_add_f32_e32 v32, v32, v33
	v_mov_b32_e32 v33, v32
	s_nop 1
	v_permlane32_swap_b32_e32 v33, v32
	s_and_saveexec_b64 s[0:1], s[2:3]
	s_cbranch_execz .LBB0_146
	s_waitcnt lgkmcnt(0)
	v_add_f32_e32 v32, v32, v33
	ds_write_b32 v113, v32 offset:1088
.LBB0_146:
	s_or_b64 exec, exec, s[0:1]
	ds_read_b32 v126, v144 offset:128
	s_waitcnt lgkmcnt(0)
	v_mul_f32_e32 v35, v25, v126
	v_mul_f32_e32 v117, v24, v126
	v_mul_f32_e32 v34, v26, v126
	v_pk_mul_f32 v[32:33], v[28:29], v[126:127] op_sel_hi:[1,0]
	v_mul_f32_e32 v29, v35, v35
	v_mov_b32_e32 v26, v31
	v_fmac_f32_e32 v29, v117, v117
	v_mul_f32_e32 v28, v30, v126
	v_pk_mul_f32 v[30:31], v[26:27], v[126:127] op_sel_hi:[1,0]
	v_fmac_f32_e32 v29, v34, v34
	v_pk_mul_f32 v[26:27], v[30:31], v[30:31]
	v_pk_mul_f32 v[24:25], v[32:33], v[32:33]
	v_add_f32_e32 v27, v27, v29
	v_add_f32_e32 v24, v24, v27
	v_add_f32_e32 v24, v25, v24
	v_fmac_f32_e32 v24, v28, v28
	v_add_f32_e32 v24, v26, v24
	v_pk_mul_f32 v[26:27], v[20:21], v[126:127] op_sel_hi:[1,0]
	s_nop 0
	v_pk_mul_f32 v[20:21], v[26:27], v[26:27]
	s_nop 0
	v_add_f32_e32 v20, v20, v24
	v_pk_mul_f32 v[24:25], v[22:23], v[126:127] op_sel_hi:[1,0]
	v_add_f32_e32 v29, v21, v20
	v_pk_mul_f32 v[20:21], v[24:25], v[24:25]
	v_pk_mul_f32 v[22:23], v[16:17], v[126:127] op_sel_hi:[1,0]
	v_add_f32_e32 v20, v20, v29
	v_add_f32_e32 v20, v21, v20
	v_pk_mul_f32 v[16:17], v[22:23], v[22:23]
	s_nop 0
	v_add_f32_e32 v16, v16, v20
	v_pk_mul_f32 v[20:21], v[18:19], v[126:127] op_sel_hi:[1,0]
	v_add_f32_e32 v29, v17, v16
	v_pk_mul_f32 v[16:17], v[20:21], v[20:21]
	s_nop 0
	v_add_f32_e32 v16, v16, v29
	v_add_f32_e32 v16, v17, v16
	v_mov_b32_e32 v17, v16
	s_nop 1
	v_permlane16_swap_b32_e32 v17, v16
	s_waitcnt lgkmcnt(0)
	v_add_f32_e32 v16, v16, v17
	v_mov_b32_e32 v17, v16
	s_nop 1
	v_permlane32_swap_b32_e32 v17, v16
	s_and_saveexec_b64 s[0:1], s[2:3]
	s_cbranch_execz .LBB0_148
	s_waitcnt lgkmcnt(0)
	v_add_f32_e32 v16, v16, v17
	ds_write_b32 v113, v16 offset:1152
.LBB0_148:
	s_or_b64 exec, exec, s[0:1]
	ds_read_b32 v126, v144 offset:192
	s_waitcnt lgkmcnt(0)
	v_mul_f32_e32 v19, v9, v126
	v_mul_f32_e32 v65, v8, v126
	v_mul_f32_e32 v18, v10, v126
	v_pk_mul_f32 v[16:17], v[12:13], v[126:127] op_sel_hi:[1,0]
	v_mul_f32_e32 v13, v19, v19
	v_mov_b32_e32 v10, v15
	v_fmac_f32_e32 v13, v65, v65
	v_pk_mul_f32 v[10:11], v[10:11], v[126:127] op_sel_hi:[1,0]
	v_fmac_f32_e32 v13, v18, v18
	v_mul_f32_e32 v12, v14, v126
	v_pk_mul_f32 v[14:15], v[10:11], v[10:11]
	v_pk_mul_f32 v[8:9], v[16:17], v[16:17]
	v_add_f32_e32 v13, v15, v13
	v_add_f32_e32 v8, v8, v13
	v_add_f32_e32 v8, v9, v8
	v_fmac_f32_e32 v8, v12, v12
	v_add_f32_e32 v13, v14, v8
	v_pk_mul_f32 v[8:9], v[4:5], v[126:127] op_sel_hi:[1,0]
	v_pk_mul_f32 v[6:7], v[6:7], v[126:127] op_sel_hi:[1,0]
	v_pk_mul_f32 v[4:5], v[8:9], v[8:9]
	s_nop 0
	v_add_f32_e32 v4, v4, v13
	v_add_f32_e32 v13, v5, v4
	v_pk_mul_f32 v[4:5], v[6:7], v[6:7]
	s_nop 0
	v_add_f32_e32 v4, v4, v13
	v_add_f32_e32 v13, v5, v4
	v_pk_mul_f32 v[4:5], v[0:1], v[126:127] op_sel_hi:[1,0]
	s_nop 0
	v_pk_mul_f32 v[0:1], v[4:5], v[4:5]
	s_nop 0
	v_add_f32_e32 v0, v0, v13
	v_add_f32_e32 v13, v1, v0
	v_pk_mul_f32 v[0:1], v[2:3], v[126:127] op_sel_hi:[1,0]
	s_nop 0
	v_pk_mul_f32 v[2:3], v[0:1], v[0:1]
	s_nop 0
	v_add_f32_e32 v2, v2, v13
	v_add_f32_e32 v2, v3, v2
	v_mov_b32_e32 v3, v2
	s_nop 1
	v_permlane16_swap_b32_e32 v3, v2
	s_waitcnt lgkmcnt(0)
	v_add_f32_e32 v2, v2, v3
	v_mov_b32_e32 v3, v2
	s_nop 1
	v_permlane32_swap_b32_e32 v3, v2
	s_and_saveexec_b64 s[0:1], s[2:3]
	s_cbranch_execz .LBB0_150
	s_waitcnt lgkmcnt(0)
	v_add_f32_e32 v2, v2, v3
	ds_write_b32 v113, v2 offset:1216

; DI float lo2f(unsigned w) { return __uint_as_float(w << 16); }
; DI float hi2f(unsigned w) { return __uint_as_float(w & 0xffff0000u); }
; DI void st4(u16* p, float a, float b, float c, float d) { uint2 v; v.x = pack2(a, b); v.y = pack2(c, d); *reinterpret_cast<uint2*>(p) = v; }
; DI float red4(float v) { v += __shfl_xor(v, 16); v += __shfl_xor(v, 32); return v; }
; DI void prep_mla_tile(const Params& P, int l, int tt, char* lds, float* s_r, float* s_ss) {
;     ...
;       for (int j = 0; j < 4; ++j) {
;         const int tl = wb * 64 + 16 * j + jn, tok = tok0 + tl, pos = tok & (S - 1);
;         const float rkv = s_r[128 + tl];
;         const uint2 pl = ld4(proj + (size_t)tok * DINP + C_KPE + 4 * q);
;         const uint2 ph = ld4(proj + (size_t)tok * DINP + C_KPE + 16 + 4 * q);
;         const float kl[4] = {lo2f(pl.x), hi2f(pl.x), lo2f(pl.y), hi2f(pl.y)};
;         const float kh[4] = {lo2f(ph.x), hi2f(ph.x), lo2f(ph.y), hi2f(ph.y)};
;         float ss = 0.f;
; #pragma unroll
;         for (int i = 0; i < 4; ++i)
; #pragma unroll
;           for (int r = 0; r < 4; ++r) { const float v = acc[i][j][r] * rkv; acc[i][j][r] = v; ss += v * v; }
; #pragma unroll
;         for (int r = 0; r < 4; ++r) ss += kl[r] * kl[r] + kh[r] * kh[r];
;         ss = red4(ss);
;         const float rs = rsqrtf(ss * (1.0f / 96) + EPS);
; #pragma unroll
;         for (int i = 0; i < 4; ++i) {
;           const int d = 16 * i + 4 * q;
;           st4(mk + (size_t)tok * 576 + h * 96 + d, acc[i][j][0] * rs * gk[d], acc[i][j][1] * rs * gk[d + 1], acc[i][j][2] * rs * gk[d + 2], acc[i][j][3] * rs * gk[d + 3]);
;         }
;         float y1[4], y2[4];
; #pragma unroll
;         for (int r = 0; r < 4; ++r) {
;           const float2 cs = r32[pos * 16 + 4 * q + r];
;           const float x1 = kl[r] * rs * gk[64 + 4 * q + r], x2 = kh[r] * rs * gk[80 + 4 * q + r];
;           y1[r] = x1 * cs.x - x2 * cs.y; y2[r] = x2 * cs.x + x1 * cs.y;
;         }
;         st4(mk + (size_t)tok * 576 + h * 96 + 64 + 4 * q, y1[0], y1[1], y1[2], y1[3]);
;         st4(mk + (size_t)tok * 576 + h * 96 + 80 + 4 * q, y2[0], y2[1], y2[2], y2[3]);
.LBB0_170:
	s_andn2_b64 vcc, exec, s[36:37]
	s_cbranch_vccnz .LBB0_167
	global_load_dwordx2 v[146:147], v[106:107], off
	global_load_dwordx2 v[148:149], v[108:109], off
	global_load_dwordx4 v[134:137], v[110:111], off
	ds_read2_b32 v[126:127], v144 offset0:128 offset1:144
	s_mul_i32 s36, s31, 0x60
	s_ashr_i32 s37, s36, 31
	s_lshl_b64 s[36:37], s[36:37], 1
	s_add_u32 s36, s71, s36
	s_waitcnt lgkmcnt(0)
	v_pk_mul_f32 v[60:61], v[60:61], v[126:127] op_sel_hi:[1,0]
	v_pk_mul_f32 v[62:63], v[62:63], v[126:127] op_sel_hi:[1,0]
	v_pk_mul_f32 v[158:159], v[50:51], v[126:127] op_sel_hi:[1,0]
	v_pk_mul_f32 v[50:51], v[60:61], v[60:61]
	v_pk_mul_f32 v[160:161], v[48:49], v[126:127] op_sel_hi:[1,0]
	v_pk_mul_f32 v[48:49], v[62:63], v[62:63]
	v_add_f32_e32 v50, v50, v51
	v_pk_mul_f32 v[152:153], v[56:57], v[126:127] op_sel_hi:[1,0]
	v_add_f32_e32 v48, v48, v50
	v_pk_mul_f32 v[154:155], v[54:55], v[126:127] op_sel_hi:[1,0]
	v_pk_mul_f32 v[54:55], v[152:153], v[152:153]
	v_add_f32_e32 v48, v49, v48
	v_pk_mul_f32 v[150:151], v[58:59], v[126:127] op_sel_hi:[1,0]
	v_add_f32_e32 v48, v54, v48
	v_pk_mul_f32 v[156:157], v[52:53], v[126:127] op_sel_hi:[1,0]
	v_pk_mul_f32 v[52:53], v[150:151], v[150:151]
	v_add_f32_e32 v48, v55, v48
	v_add_f32_e32 v48, v52, v48
	v_pk_mul_f32 v[58:59], v[156:157], v[156:157]
	v_add_f32_e32 v48, v53, v48
	v_add_f32_e32 v48, v58, v48
	v_pk_mul_f32 v[56:57], v[154:155], v[154:155]
	v_add_f32_e32 v48, v59, v48
	v_add_f32_e32 v48, v56, v48
	v_pk_mul_f32 v[170:171], v[160:161], v[160:161]
	v_add_f32_e32 v48, v57, v48
	v_add_f32_e32 v48, v170, v48
	v_pk_mul_f32 v[164:165], v[158:159], v[158:159]
	v_add_f32_e32 v48, v171, v48
	v_add_f32_e32 v48, v164, v48
	v_add_f32_e32 v126, v165, v48
	s_addc_u32 s37, s72, s37
	s_waitcnt vmcnt(2)
	v_lshlrev_b32_e32 v51, 16, v146
	s_waitcnt vmcnt(1)
	v_lshlrev_b32_e32 v59, 16, v148
	v_and_b32_e32 v58, 0xffff0000, v148
	v_and_b32_e32 v50, 0xffff0000, v146
	v_pk_mul_f32 v[52:53], v[58:59], v[58:59]
	v_lshlrev_b32_e32 v57, 16, v149
	v_and_b32_e32 v56, 0xffff0000, v149
	v_pk_fma_f32 v[52:53], v[50:51], v[50:51], v[52:53]
	v_lshlrev_b32_e32 v49, 16, v147
	v_and_b32_e32 v48, 0xffff0000, v147
	v_pk_mul_f32 v[54:55], v[56:57], v[56:57]
	v_add_f32_e32 v53, v53, v126
	v_pk_fma_f32 v[54:55], v[48:49], v[48:49], v[54:55]
	v_add_f32_e32 v52, v52, v53
	v_add_f32_e32 v52, v55, v52
	v_add_f32_e32 v52, v54, v52
	v_mov_b32_e32 v53, v52
	s_nop 1
	v_permlane16_swap_b32_e32 v53, v52
	s_waitcnt lgkmcnt(0)
	v_add_f32_e32 v52, v52, v53
	v_mov_b32_e32 v53, v52
	s_nop 1
	v_permlane32_swap_b32_e32 v53, v52
	s_waitcnt lgkmcnt(0)
	v_add_f32_e32 v52, v52, v53
	v_fmamk_f32 v52, v52, 0x3c2aaaab, v128
	v_mul_f32_e32 v53, 0x4b800000, v52
	v_cmp_gt_f32_e32 vcc, s57, v52
	s_nop 1
	v_cndmask_b32_e32 v52, v52, v53, vcc
	v_rsq_f32_e32 v54, v52
	v_lshl_add_u64 v[52:53], s[36:37], 0, v[70:71]
	v_lshl_add_u64 v[164:165], v[52:53], 0, v[132:133]
	v_mul_f32_e32 v52, 0x45800000, v54
	v_cndmask_b32_e32 v126, v54, v52, vcc
	v_pk_mul_f32 v[52:53], v[60:61], v[126:127] op_sel_hi:[1,0]
	v_pk_mul_f32 v[54:55], v[62:63], v[126:127] op_sel_hi:[1,0]
	s_waitcnt vmcnt(0)
	v_pk_mul_f32 v[52:53], v[134:135], v[52:53]
	v_pk_mul_f32 v[54:55], v[136:137], v[54:55]
	v_cvt_pk_bf16_f32 v52, v52, v53
	v_cvt_pk_bf16_f32 v53, v54, v55
	global_store_dwordx2 v[164:165], v[52:53], off
	global_load_dwordx4 v[52:55], v[110:111], off offset:64
	v_pk_mul_f32 v[60:61], v[152:153], v[126:127] op_sel_hi:[1,0]
	v_pk_mul_f32 v[62:63], v[150:151], v[126:127] op_sel_hi:[1,0]
	v_pk_mul_f32 v[58:59], v[126:127], v[58:59] op_sel_hi:[0,1]
	v_pk_mul_f32 v[56:57], v[126:127], v[56:57] op_sel_hi:[0,1]
	v_pk_mul_f32 v[50:51], v[126:127], v[50:51] op_sel_hi:[0,1]
	v_pk_mul_f32 v[48:49], v[126:127], v[48:49] op_sel_hi:[0,1]
	s_waitcnt vmcnt(0)
	v_pk_mul_f32 v[52:53], v[52:53], v[60:61]
	v_pk_mul_f32 v[54:55], v[54:55], v[62:63]
	v_cvt_pk_bf16_f32 v52, v52, v53
	v_cvt_pk_bf16_f32 v53, v54, v55
	global_store_dwordx2 v[164:165], v[52:53], off offset:32
	global_load_dwordx4 v[52:55], v[110:111], off offset:128
	v_pk_mul_f32 v[60:61], v[156:157], v[126:127] op_sel_hi:[1,0]
	v_pk_mul_f32 v[62:63], v[154:155], v[126:127] op_sel_hi:[1,0]
	s_waitcnt vmcnt(0)
	v_pk_mul_f32 v[52:53], v[52:53], v[60:61]
	v_pk_mul_f32 v[54:55], v[54:55], v[62:63]
	v_cvt_pk_bf16_f32 v52, v52, v53
	v_cvt_pk_bf16_f32 v53, v54, v55
	global_store_dwordx2 v[164:165], v[52:53], off offset:64
	global_load_dwordx4 v[52:55], v[110:111], off offset:192
	v_pk_mul_f32 v[60:61], v[160:161], v[126:127] op_sel_hi:[1,0]
	v_pk_mul_f32 v[62:63], v[158:159], v[126:127] op_sel_hi:[1,0]
	s_waitcnt vmcnt(0)
	v_pk_mul_f32 v[52:53], v[52:53], v[60:61]
	v_pk_mul_f32 v[54:55], v[54:55], v[62:63]
	v_cvt_pk_bf16_f32 v52, v52, v53
	v_cvt_pk_bf16_f32 v53, v54, v55
	global_store_dwordx2 v[164:165], v[52:53], off offset:96
	global_load_dwordx4 v[60:63], v[110:111], off offset:320
	global_load_dwordx4 v[134:137], v[110:111], off offset:256
	global_load_dwordx4 v[146:149], v[68:69], off
	global_load_dwordx4 v[150:153], v[68:69], off offset:16
	global_load_dwordx2 v[54:55], v[112:113], off
	global_load_dwordx2 v[52:53], v[114:115], off
	s_waitcnt vmcnt(5)
	v_pk_mul_f32 v[58:59], v[58:59], v[60:61] op_sel:[1,0] op_sel_hi:[0,1]
	v_pk_mul_f32 v[56:57], v[56:57], v[62:63] op_sel:[1,0] op_sel_hi:[0,1]
	s_waitcnt vmcnt(3)
	v_mov_b32_e32 v60, v146
	v_mov_b32_e32 v61, v148
	v_mov_b32_e32 v148, v147
	s_waitcnt vmcnt(2)
; DI float lo2f(unsigned w) { return __uint_as_float(w << 16); }
; DI float hi2f(unsigned w) { return __uint_as_float(w & 0xffff0000u); }
; DI void st4(u16* p, float a, float b, float c, float d) { uint2 v; v.x = pack2(a, b); v.y = pack2(c, d); *reinterpret_cast<uint2*>(p) = v; }
; DI float red4(float v) { v += __shfl_xor(v, 16); v += __shfl_xor(v, 32); return v; }
; DI void prep_mla_tile(const Params& P, int l, int tt, char* lds, float* s_r, float* s_ss) {
;     ...
;       for (int j = 0; j < 4; ++j) {
;         const int tl = wb * 64 + 16 * j + jn, tok = tok0 + tl, pos = tok & (S - 1);
;         const float rkv = s_r[128 + tl];
;         const uint2 pl = ld4(proj + (size_t)tok * DINP + C_KPE + 4 * q);
;         const uint2 ph = ld4(proj + (size_t)tok * DINP + C_KPE + 16 + 4 * q);
;         const float kl[4] = {lo2f(pl.x), hi2f(pl.x), lo2f(pl.y), hi2f(pl.y)};
;         const float kh[4] = {lo2f(ph.x), hi2f(ph.x), lo2f(ph.y), hi2f(ph.y)};
;         float ss = 0.f;
; #pragma unroll
;         for (int i = 0; i < 4; ++i)
; #pragma unroll
;           for (int r = 0; r < 4; ++r) { const float v = acc[i][j][r] * rkv; acc[i][j][r] = v; ss += v * v; }
; #pragma unroll
;         for (int r = 0; r < 4; ++r) ss += kl[r] * kl[r] + kh[r] * kh[r];
;         ss = red4(ss);
;         const float rs = rsqrtf(ss * (1.0f / 96) + EPS);
; #pragma unroll
;         for (int i = 0; i < 4; ++i) {
;           const int d = 16 * i + 4 * q;
;           st4(mk + (size_t)tok * 576 + h * 96 + d, acc[i][j][0] * rs * gk[d], acc[i][j][1] * rs * gk[d + 1], acc[i][j][2] * rs * gk[d + 2], acc[i][j][3] * rs * gk[d + 3]);
;         }
;         float y1[4], y2[4];
; #pragma unroll
;         for (int r = 0; r < 4; ++r) {
;           const float2 cs = r32[pos * 16 + 4 * q + r];
;           const float x1 = kl[r] * rs * gk[64 + 4 * q + r], x2 = kh[r] * rs * gk[80 + 4 * q + r];
;           y1[r] = x1 * cs.x - x2 * cs.y; y2[r] = x2 * cs.x + x1 * cs.y;
;         }
;         st4(mk + (size_t)tok * 576 + h * 96 + 64 + 4 * q, y1[0], y1[1], y1[2], y1[3]);
;         st4(mk + (size_t)tok * 576 + h * 96 + 80 + 4 * q, y2[0], y2[1], y2[2], y2[3]);
	v_mov_b32_e32 v63, v152
	v_mov_b32_e32 v152, v151
	v_pk_mul_f32 v[50:51], v[50:51], v[134:135] op_sel:[1,0] op_sel_hi:[0,1]
	v_pk_mul_f32 v[48:49], v[48:49], v[136:137] op_sel:[1,0] op_sel_hi:[0,1]
	v_mov_b32_e32 v62, v150
	v_pk_mul_f32 v[134:135], v[148:149], v[58:59]
	v_pk_mul_f32 v[58:59], v[60:61], v[58:59]
	v_pk_mul_f32 v[136:137], v[152:153], v[56:57]
	v_pk_mul_f32 v[56:57], v[62:63], v[56:57]
	v_pk_fma_f32 v[60:61], v[60:61], v[50:51], v[134:135] neg_lo:[0,0,1] neg_hi:[0,0,1]
	v_pk_fma_f32 v[50:51], v[148:149], v[50:51], v[58:59]
	v_pk_fma_f32 v[58:59], v[62:63], v[48:49], v[136:137] neg_lo:[0,0,1] neg_hi:[0,0,1]
	v_pk_fma_f32 v[48:49], v[152:153], v[48:49], v[56:57]
	v_cvt_pk_bf16_f32 v56, v60, v61
	v_cvt_pk_bf16_f32 v57, v58, v59
	v_cvt_pk_bf16_f32 v50, v50, v51
	v_cvt_pk_bf16_f32 v51, v48, v49
	global_store_dwordx2 v[164:165], v[56:57], off offset:128
	global_store_dwordx2 v[164:165], v[50:51], off offset:160
	global_load_dwordx4 v[48:51], v[110:111], off
	s_nop 0
	global_load_dwordx2 v[58:59], v[116:117], off
	global_load_dwordx2 v[56:57], v[118:119], off
	v_mov_b32_e32 v60, v127
	v_pk_mul_f32 v[32:33], v[32:33], v[60:61] op_sel_hi:[1,0]
	v_pk_mul_f32 v[34:35], v[34:35], v[60:61] op_sel_hi:[1,0]
	v_pk_mul_f32 v[62:63], v[32:33], v[32:33]
	v_pk_mul_f32 v[38:39], v[38:39], v[60:61] op_sel_hi:[1,0]
	v_pk_mul_f32 v[36:37], v[36:37], v[60:61] op_sel_hi:[1,0]
	v_pk_mul_f32 v[42:43], v[42:43], v[60:61] op_sel_hi:[1,0]
	v_pk_mul_f32 v[40:41], v[40:41], v[60:61] op_sel_hi:[1,0]
	v_pk_mul_f32 v[46:47], v[46:47], v[60:61] op_sel_hi:[1,0]
	v_pk_mul_f32 v[44:45], v[44:45], v[60:61] op_sel_hi:[1,0]
	v_pk_mul_f32 v[60:61], v[34:35], v[34:35]
	v_add_f32_e32 v62, v62, v63
	v_add_f32_e32 v60, v60, v62
	v_pk_mul_f32 v[134:135], v[36:37], v[36:37]
	v_add_f32_e32 v60, v61, v60
	v_add_f32_e32 v60, v134, v60
	v_pk_mul_f32 v[126:127], v[38:39], v[38:39]
	v_add_f32_e32 v60, v135, v60
	v_add_f32_e32 v60, v126, v60
	v_pk_mul_f32 v[146:147], v[40:41], v[40:41]
	v_add_f32_e32 v60, v127, v60
	v_add_f32_e32 v60, v146, v60
	v_pk_mul_f32 v[136:137], v[42:43], v[42:43]
	v_add_f32_e32 v60, v147, v60
	v_add_f32_e32 v60, v136, v60
	v_pk_mul_f32 v[150:151], v[44:45], v[44:45]
	v_add_f32_e32 v60, v137, v60
	v_add_f32_e32 v60, v150, v60
	v_pk_mul_f32 v[148:149], v[46:47], v[46:47]
	v_add_f32_e32 v60, v151, v60
	v_add_f32_e32 v60, v148, v60
	v_add_f32_e32 v136, v149, v60
	s_waitcnt vmcnt(6)
	v_lshlrev_b32_e32 v61, 16, v54
	v_and_b32_e32 v60, 0xffff0000, v54
	v_lshlrev_b32_e32 v63, 16, v55
	v_and_b32_e32 v62, 0xffff0000, v55
	s_waitcnt vmcnt(5)
	v_lshlrev_b32_e32 v55, 16, v52
	v_and_b32_e32 v54, 0xffff0000, v52
	v_lshlrev_b32_e32 v127, 16, v53
	v_and_b32_e32 v126, 0xffff0000, v53
	v_pk_mul_f32 v[52:53], v[54:55], v[54:55]
	v_pk_mul_f32 v[134:135], v[126:127], v[126:127]
	v_pk_fma_f32 v[52:53], v[60:61], v[60:61], v[52:53]
	v_pk_fma_f32 v[134:135], v[62:63], v[62:63], v[134:135]
	v_add_f32_e32 v53, v53, v136
	v_add_f32_e32 v52, v52, v53
	v_add_f32_e32 v52, v135, v52
	v_add_f32_e32 v52, v134, v52
	v_mov_b32_e32 v53, v52
	s_nop 1
	v_permlane16_swap_b32_e32 v53, v52
	s_waitcnt lgkmcnt(0)
	v_add_f32_e32 v52, v52, v53
	v_mov_b32_e32 v53, v52
	s_nop 1
	v_permlane32_swap_b32_e32 v53, v52
	s_waitcnt lgkmcnt(0)
	v_add_f32_e32 v52, v52, v53
	v_fmamk_f32 v52, v52, 0x3c2aaaab, v128
	v_mul_f32_e32 v53, 0x4b800000, v52
	v_cmp_gt_f32_e32 vcc, s57, v52
	s_nop 1
	v_cndmask_b32_e32 v52, v52, v53, vcc
	v_rsq_f32_e32 v134, v52
	v_lshl_add_u64 v[52:53], s[36:37], 0, v[74:75]
	v_lshl_add_u64 v[52:53], v[52:53], 0, v[132:133]
	v_mul_f32_e32 v135, 0x45800000, v134
	v_cndmask_b32_e32 v134, v134, v135, vcc
	v_pk_mul_f32 v[32:33], v[32:33], v[134:135] op_sel_hi:[1,0]
	v_pk_mul_f32 v[34:35], v[34:35], v[134:135] op_sel_hi:[1,0]
	v_pk_mul_f32 v[36:37], v[36:37], v[134:135] op_sel_hi:[1,0]
	v_pk_mul_f32 v[38:39], v[38:39], v[134:135] op_sel_hi:[1,0]
	s_waitcnt vmcnt(2)
	v_pk_mul_f32 v[32:33], v[48:49], v[32:33]
	v_pk_mul_f32 v[34:35], v[50:51], v[34:35]
	v_cvt_pk_bf16_f32 v32, v32, v33
	v_cvt_pk_bf16_f32 v33, v34, v35
	global_store_dwordx2 v[52:53], v[32:33], off
	global_load_dwordx4 v[32:35], v[110:111], off offset:64
	v_pk_mul_f32 v[48:49], v[134:135], v[54:55] op_sel_hi:[0,1]
	v_pk_mul_f32 v[54:55], v[134:135], v[126:127] op_sel_hi:[0,1]
	v_pk_mul_f32 v[50:51], v[134:135], v[60:61] op_sel_hi:[0,1]
	v_pk_mul_f32 v[60:61], v[134:135], v[62:63] op_sel_hi:[0,1]
	s_waitcnt vmcnt(0)
	v_pk_mul_f32 v[32:33], v[32:33], v[36:37]
	v_pk_mul_f32 v[34:35], v[34:35], v[38:39]
	v_cvt_pk_bf16_f32 v32, v32, v33
	v_cvt_pk_bf16_f32 v33, v34, v35
	global_store_dwordx2 v[52:53], v[32:33], off offset:32
	global_load_dwordx4 v[32:35], v[110:111], off offset:128
	v_pk_mul_f32 v[36:37], v[40:41], v[134:135] op_sel_hi:[1,0]
	v_pk_mul_f32 v[38:39], v[42:43], v[134:135] op_sel_hi:[1,0]
	s_waitcnt vmcnt(0)
	v_pk_mul_f32 v[32:33], v[32:33], v[36:37]
	v_pk_mul_f32 v[34:35], v[34:35], v[38:39]
	v_cvt_pk_bf16_f32 v32, v32, v33
	v_cvt_pk_bf16_f32 v33, v34, v35
	global_store_dwordx2 v[52:53], v[32:33], off offset:64
	global_load_dwordx4 v[32:35], v[110:111], off offset:192
	v_pk_mul_f32 v[36:37], v[44:45], v[134:135] op_sel_hi:[1,0]
	v_pk_mul_f32 v[38:39], v[46:47], v[134:135] op_sel_hi:[1,0]
	s_waitcnt vmcnt(0)
	v_pk_mul_f32 v[32:33], v[32:33], v[36:37]
	v_pk_mul_f32 v[34:35], v[34:35], v[38:39]
	v_cvt_pk_bf16_f32 v32, v32, v33
	v_cvt_pk_bf16_f32 v33, v34, v35
	global_store_dwordx2 v[52:53], v[32:33], off offset:96
	global_load_dwordx4 v[32:35], v[110:111], off offset:320
	s_nop 0
	global_load_dwordx4 v[36:39], v[110:111], off offset:256
	global_load_dwordx4 v[40:43], v[72:73], off
	global_load_dwordx4 v[44:47], v[72:73], off offset:16
	s_waitcnt vmcnt(3)
; DI float lo2f(unsigned w) { return __uint_as_float(w << 16); }
; DI float hi2f(unsigned w) { return __uint_as_float(w & 0xffff0000u); }
; DI void st4(u16* p, float a, float b, float c, float d) { uint2 v; v.x = pack2(a, b); v.y = pack2(c, d); *reinterpret_cast<uint2*>(p) = v; }
; DI float red4(float v) { v += __shfl_xor(v, 16); v += __shfl_xor(v, 32); return v; }
; DI void prep_mla_tile(const Params& P, int l, int tt, char* lds, float* s_r, float* s_ss) {
;     ...
;       for (int j = 0; j < 4; ++j) {
;         const int tl = wb * 64 + 16 * j + jn, tok = tok0 + tl, pos = tok & (S - 1);
;         const float rkv = s_r[128 + tl];
;         const uint2 pl = ld4(proj + (size_t)tok * DINP + C_KPE + 4 * q);
;         const uint2 ph = ld4(proj + (size_t)tok * DINP + C_KPE + 16 + 4 * q);
;         const float kl[4] = {lo2f(pl.x), hi2f(pl.x), lo2f(pl.y), hi2f(pl.y)};
;         const float kh[4] = {lo2f(ph.x), hi2f(ph.x), lo2f(ph.y), hi2f(ph.y)};
;         float ss = 0.f;
; #pragma unroll
;         for (int i = 0; i < 4; ++i)
; #pragma unroll
;           for (int r = 0; r < 4; ++r) { const float v = acc[i][j][r] * rkv; acc[i][j][r] = v; ss += v * v; }
; #pragma unroll
;         for (int r = 0; r < 4; ++r) ss += kl[r] * kl[r] + kh[r] * kh[r];
;         ss = red4(ss);
;         const float rs = rsqrtf(ss * (1.0f / 96) + EPS);
; #pragma unroll
;         for (int i = 0; i < 4; ++i) {
;           const int d = 16 * i + 4 * q;
;           st4(mk + (size_t)tok * 576 + h * 96 + d, acc[i][j][0] * rs * gk[d], acc[i][j][1] * rs * gk[d + 1], acc[i][j][2] * rs * gk[d + 2], acc[i][j][3] * rs * gk[d + 3]);
;         }
;         float y1[4], y2[4];
; #pragma unroll
;         for (int r = 0; r < 4; ++r) {
;           const float2 cs = r32[pos * 16 + 4 * q + r];
;           const float x1 = kl[r] * rs * gk[64 + 4 * q + r], x2 = kh[r] * rs * gk[80 + 4 * q + r];
;           y1[r] = x1 * cs.x - x2 * cs.y; y2[r] = x2 * cs.x + x1 * cs.y;
;         }
;         st4(mk + (size_t)tok * 576 + h * 96 + 64 + 4 * q, y1[0], y1[1], y1[2], y1[3]);
;         st4(mk + (size_t)tok * 576 + h * 96 + 80 + 4 * q, y2[0], y2[1], y2[2], y2[3]);
	v_pk_mul_f32 v[32:33], v[48:49], v[32:33] op_sel:[1,0] op_sel_hi:[0,1]
	v_pk_mul_f32 v[34:35], v[54:55], v[34:35] op_sel:[1,0] op_sel_hi:[0,1]
	s_waitcnt vmcnt(1)
	v_mov_b32_e32 v48, v40
	v_mov_b32_e32 v49, v42
	v_mov_b32_e32 v42, v41
	s_waitcnt vmcnt(0)
	v_mov_b32_e32 v41, v46
	v_mov_b32_e32 v46, v45
	v_pk_mul_f32 v[36:37], v[50:51], v[36:37] op_sel:[1,0] op_sel_hi:[0,1]
	v_pk_mul_f32 v[38:39], v[60:61], v[38:39] op_sel:[1,0] op_sel_hi:[0,1]
	v_mov_b32_e32 v40, v44
	v_pk_mul_f32 v[44:45], v[42:43], v[32:33]
	v_pk_mul_f32 v[32:33], v[48:49], v[32:33]
	v_pk_mul_f32 v[50:51], v[46:47], v[34:35]
	v_pk_mul_f32 v[34:35], v[40:41], v[34:35]
	v_pk_fma_f32 v[44:45], v[48:49], v[36:37], v[44:45] neg_lo:[0,0,1] neg_hi:[0,0,1]
	v_pk_fma_f32 v[32:33], v[42:43], v[36:37], v[32:33]
	v_pk_fma_f32 v[36:37], v[40:41], v[38:39], v[50:51] neg_lo:[0,0,1] neg_hi:[0,0,1]
	v_pk_fma_f32 v[34:35], v[46:47], v[38:39], v[34:35]
	v_cvt_pk_bf16_f32 v38, v44, v45
	v_cvt_pk_bf16_f32 v39, v36, v37
	v_cvt_pk_bf16_f32 v32, v32, v33
	v_cvt_pk_bf16_f32 v33, v34, v35
	global_store_dwordx2 v[52:53], v[38:39], off offset:128
	global_store_dwordx2 v[52:53], v[32:33], off offset:160
	global_load_dwordx4 v[34:37], v[110:111], off
	ds_read2_b32 v[32:33], v144 offset0:160 offset1:176
	s_waitcnt lgkmcnt(0)
	v_pk_mul_f32 v[28:29], v[28:29], v[32:33] op_sel_hi:[1,0]
	v_pk_mul_f32 v[30:31], v[30:31], v[32:33] op_sel_hi:[1,0]
	v_pk_mul_f32 v[46:47], v[18:19], v[32:33] op_sel_hi:[1,0]
	v_pk_mul_f32 v[18:19], v[28:29], v[28:29]
	v_pk_mul_f32 v[48:49], v[16:17], v[32:33] op_sel_hi:[1,0]
	v_pk_mul_f32 v[16:17], v[30:31], v[30:31]
	v_add_f32_e32 v18, v18, v19
	v_pk_mul_f32 v[40:41], v[24:25], v[32:33] op_sel_hi:[1,0]
	v_add_f32_e32 v16, v16, v18
	v_pk_mul_f32 v[42:43], v[22:23], v[32:33] op_sel_hi:[1,0]
	v_pk_mul_f32 v[22:23], v[40:41], v[40:41]
	v_add_f32_e32 v16, v17, v16
	v_pk_mul_f32 v[38:39], v[26:27], v[32:33] op_sel_hi:[1,0]
	v_add_f32_e32 v16, v22, v16
	v_pk_mul_f32 v[44:45], v[20:21], v[32:33] op_sel_hi:[1,0]
	v_pk_mul_f32 v[20:21], v[38:39], v[38:39]
	v_add_f32_e32 v16, v23, v16
	v_add_f32_e32 v16, v20, v16
	v_pk_mul_f32 v[26:27], v[44:45], v[44:45]
	v_add_f32_e32 v16, v21, v16
	v_add_f32_e32 v16, v26, v16
	v_pk_mul_f32 v[24:25], v[42:43], v[42:43]
	v_add_f32_e32 v16, v27, v16
	v_add_f32_e32 v16, v24, v16
	v_pk_mul_f32 v[52:53], v[48:49], v[48:49]
	v_add_f32_e32 v16, v25, v16
	v_add_f32_e32 v16, v52, v16
	v_pk_mul_f32 v[50:51], v[46:47], v[46:47]
	v_add_f32_e32 v16, v53, v16
	v_lshlrev_b32_e32 v23, 16, v56
	v_and_b32_e32 v22, 0xffff0000, v56
	v_add_f32_e32 v16, v50, v16
	v_lshlrev_b32_e32 v19, 16, v58
	v_and_b32_e32 v18, 0xffff0000, v58
	v_pk_mul_f32 v[24:25], v[22:23], v[22:23]
	v_add_f32_e32 v32, v51, v16
	v_lshlrev_b32_e32 v21, 16, v57
	v_and_b32_e32 v20, 0xffff0000, v57
	v_pk_fma_f32 v[24:25], v[18:19], v[18:19], v[24:25]
	v_lshlrev_b32_e32 v17, 16, v59
	v_and_b32_e32 v16, 0xffff0000, v59
	v_pk_mul_f32 v[26:27], v[20:21], v[20:21]
	v_add_f32_e32 v25, v25, v32
	v_pk_fma_f32 v[26:27], v[16:17], v[16:17], v[26:27]
	v_add_f32_e32 v24, v24, v25
	v_add_f32_e32 v24, v27, v24
	v_add_f32_e32 v24, v26, v24
	v_mov_b32_e32 v25, v24
	s_nop 1
	v_permlane16_swap_b32_e32 v25, v24
	s_waitcnt lgkmcnt(0)
	v_add_f32_e32 v24, v24, v25
	v_mov_b32_e32 v25, v24
	s_nop 1
	v_permlane32_swap_b32_e32 v25, v24
	s_waitcnt lgkmcnt(0)
	v_add_f32_e32 v24, v24, v25
	v_fmamk_f32 v24, v24, 0x3c2aaaab, v128
	v_mul_f32_e32 v25, 0x4b800000, v24
	v_cmp_gt_f32_e32 vcc, s57, v24
	s_nop 1
	v_cndmask_b32_e32 v24, v24, v25, vcc
	v_rsq_f32_e32 v26, v24
	v_lshl_add_u64 v[24:25], s[36:37], 0, v[78:79]
	v_lshl_add_u64 v[50:51], v[24:25], 0, v[132:133]
	v_mul_f32_e32 v24, 0x45800000, v26
	v_cndmask_b32_e32 v32, v26, v24, vcc
	v_pk_mul_f32 v[24:25], v[28:29], v[32:33] op_sel_hi:[1,0]
	v_pk_mul_f32 v[26:27], v[30:31], v[32:33] op_sel_hi:[1,0]
	v_pk_mul_f32 v[28:29], v[40:41], v[32:33] op_sel_hi:[1,0]
	s_waitcnt vmcnt(0)
	v_pk_mul_f32 v[24:25], v[34:35], v[24:25]
	v_pk_mul_f32 v[26:27], v[36:37], v[26:27]
	v_cvt_pk_bf16_f32 v24, v24, v25
	v_cvt_pk_bf16_f32 v25, v26, v27
	global_store_dwordx2 v[50:51], v[24:25], off
	global_load_dwordx4 v[24:27], v[110:111], off offset:64
	v_pk_mul_f32 v[30:31], v[38:39], v[32:33] op_sel_hi:[1,0]
	v_pk_mul_f32 v[22:23], v[32:33], v[22:23] op_sel_hi:[0,1]
	v_pk_mul_f32 v[20:21], v[32:33], v[20:21] op_sel_hi:[0,1]
	v_pk_mul_f32 v[18:19], v[32:33], v[18:19] op_sel_hi:[0,1]
	v_pk_mul_f32 v[16:17], v[32:33], v[16:17] op_sel_hi:[0,1]
	s_waitcnt vmcnt(0)
	v_pk_mul_f32 v[24:25], v[24:25], v[28:29]
	v_pk_mul_f32 v[26:27], v[26:27], v[30:31]
	v_cvt_pk_bf16_f32 v24, v24, v25
	v_cvt_pk_bf16_f32 v25, v26, v27
	global_store_dwordx2 v[50:51], v[24:25], off offset:32
	global_load_dwordx4 v[24:27], v[110:111], off offset:128
	v_pk_mul_f32 v[28:29], v[44:45], v[32:33] op_sel_hi:[1,0]
	v_pk_mul_f32 v[30:31], v[42:43], v[32:33] op_sel_hi:[1,0]
	s_waitcnt vmcnt(0)
	v_pk_mul_f32 v[24:25], v[24:25], v[28:29]
	v_pk_mul_f32 v[26:27], v[26:27], v[30:31]
	v_cvt_pk_bf16_f32 v24, v24, v25
	v_cvt_pk_bf16_f32 v25, v26, v27
	global_store_dwordx2 v[50:51], v[24:25], off offset:64
	global_load_dwordx4 v[24:27], v[110:111], off offset:192
	v_pk_mul_f32 v[28:29], v[48:49], v[32:33] op_sel_hi:[1,0]
	v_pk_mul_f32 v[30:31], v[46:47], v[32:33] op_sel_hi:[1,0]
	s_waitcnt vmcnt(0)
	v_pk_mul_f32 v[24:25], v[24:25], v[28:29]
	v_pk_mul_f32 v[26:27], v[26:27], v[30:31]
	v_cvt_pk_bf16_f32 v24, v24, v25
	v_cvt_pk_bf16_f32 v25, v26, v27
	global_store_dwordx2 v[50:51], v[24:25], off offset:96
	global_load_dwordx4 v[24:27], v[110:111], off offset:320
	s_nop 0
	global_load_dwordx4 v[28:31], v[110:111], off offset:256
	global_load_dwordx4 v[34:37], v[76:77], off
	global_load_dwordx4 v[38:41], v[76:77], off offset:16
	global_load_dwordx2 v[42:43], v[120:121], off
	global_load_dwordx2 v[44:45], v[122:123], off
	s_waitcnt vmcnt(5)
; DI float lo2f(unsigned w) { return __uint_as_float(w << 16); }
; DI float hi2f(unsigned w) { return __uint_as_float(w & 0xffff0000u); }
; DI void st4(u16* p, float a, float b, float c, float d) { uint2 v; v.x = pack2(a, b); v.y = pack2(c, d); *reinterpret_cast<uint2*>(p) = v; }
; DI float red4(float v) { v += __shfl_xor(v, 16); v += __shfl_xor(v, 32); return v; }
; DI void prep_mla_tile(const Params& P, int l, int tt, char* lds, float* s_r, float* s_ss) {
;     ...
;       for (int j = 0; j < 4; ++j) {
;         const int tl = wb * 64 + 16 * j + jn, tok = tok0 + tl, pos = tok & (S - 1);
;         const float rkv = s_r[128 + tl];
;         const uint2 pl = ld4(proj + (size_t)tok * DINP + C_KPE + 4 * q);
;         const uint2 ph = ld4(proj + (size_t)tok * DINP + C_KPE + 16 + 4 * q);
;         const float kl[4] = {lo2f(pl.x), hi2f(pl.x), lo2f(pl.y), hi2f(pl.y)};
;         const float kh[4] = {lo2f(ph.x), hi2f(ph.x), lo2f(ph.y), hi2f(ph.y)};
;         float ss = 0.f;
; #pragma unroll
;         for (int i = 0; i < 4; ++i)
; #pragma unroll
;           for (int r = 0; r < 4; ++r) { const float v = acc[i][j][r] * rkv; acc[i][j][r] = v; ss += v * v; }
; #pragma unroll
;         for (int r = 0; r < 4; ++r) ss += kl[r] * kl[r] + kh[r] * kh[r];
;         ss = red4(ss);
;         const float rs = rsqrtf(ss * (1.0f / 96) + EPS);
; #pragma unroll
;         for (int i = 0; i < 4; ++i) {
;           const int d = 16 * i + 4 * q;
;           st4(mk + (size_t)tok * 576 + h * 96 + d, acc[i][j][0] * rs * gk[d], acc[i][j][1] * rs * gk[d + 1], acc[i][j][2] * rs * gk[d + 2], acc[i][j][3] * rs * gk[d + 3]);
;         }
;         float y1[4], y2[4];
; #pragma unroll
;         for (int r = 0; r < 4; ++r) {
;           const float2 cs = r32[pos * 16 + 4 * q + r];
;           const float x1 = kl[r] * rs * gk[64 + 4 * q + r], x2 = kh[r] * rs * gk[80 + 4 * q + r];
;           y1[r] = x1 * cs.x - x2 * cs.y; y2[r] = x2 * cs.x + x1 * cs.y;
;         }
;         st4(mk + (size_t)tok * 576 + h * 96 + 64 + 4 * q, y1[0], y1[1], y1[2], y1[3]);
;         st4(mk + (size_t)tok * 576 + h * 96 + 80 + 4 * q, y2[0], y2[1], y2[2], y2[3]);
	v_pk_mul_f32 v[22:23], v[22:23], v[24:25] op_sel:[1,0] op_sel_hi:[0,1]
	v_pk_mul_f32 v[20:21], v[20:21], v[26:27] op_sel:[1,0] op_sel_hi:[0,1]
	s_waitcnt vmcnt(3)
	v_mov_b32_e32 v24, v34
	v_mov_b32_e32 v25, v36
	v_mov_b32_e32 v36, v35
	s_waitcnt vmcnt(2)
	v_mov_b32_e32 v27, v40
	v_mov_b32_e32 v40, v39
	v_pk_mul_f32 v[18:19], v[18:19], v[28:29] op_sel:[1,0] op_sel_hi:[0,1]
	v_pk_mul_f32 v[16:17], v[16:17], v[30:31] op_sel:[1,0] op_sel_hi:[0,1]
	v_mov_b32_e32 v26, v38
	v_pk_mul_f32 v[28:29], v[36:37], v[22:23]
	v_pk_mul_f32 v[22:23], v[24:25], v[22:23]
	v_pk_mul_f32 v[30:31], v[40:41], v[20:21]
	v_pk_mul_f32 v[20:21], v[26:27], v[20:21]
	v_pk_fma_f32 v[24:25], v[24:25], v[18:19], v[28:29] neg_lo:[0,0,1] neg_hi:[0,0,1]
	v_pk_fma_f32 v[18:19], v[36:37], v[18:19], v[22:23]
	v_pk_fma_f32 v[22:23], v[26:27], v[16:17], v[30:31] neg_lo:[0,0,1] neg_hi:[0,0,1]
	v_pk_fma_f32 v[16:17], v[40:41], v[16:17], v[20:21]
	v_cvt_pk_bf16_f32 v20, v24, v25
	v_cvt_pk_bf16_f32 v21, v22, v23
	v_cvt_pk_bf16_f32 v18, v18, v19
	v_cvt_pk_bf16_f32 v19, v16, v17
	global_store_dwordx2 v[50:51], v[20:21], off offset:128
	global_store_dwordx2 v[50:51], v[18:19], off offset:160
	global_load_dwordx4 v[16:19], v[110:111], off
	v_mov_b32_e32 v20, v33
	v_pk_mul_f32 v[12:13], v[12:13], v[20:21] op_sel_hi:[1,0]
	v_pk_mul_f32 v[14:15], v[14:15], v[20:21] op_sel_hi:[1,0]
	v_pk_mul_f32 v[30:31], v[2:3], v[20:21] op_sel_hi:[1,0]
	v_pk_mul_f32 v[2:3], v[12:13], v[12:13]
	v_pk_mul_f32 v[22:23], v[10:11], v[20:21] op_sel_hi:[1,0]
	v_pk_mul_f32 v[24:25], v[8:9], v[20:21] op_sel_hi:[1,0]
	v_pk_mul_f32 v[26:27], v[6:7], v[20:21] op_sel_hi:[1,0]
	v_pk_mul_f32 v[28:29], v[4:5], v[20:21] op_sel_hi:[1,0]
	v_pk_mul_f32 v[20:21], v[0:1], v[20:21] op_sel_hi:[1,0]
	v_pk_mul_f32 v[0:1], v[14:15], v[14:15]
	v_add_f32_e32 v2, v2, v3
	v_add_f32_e32 v0, v0, v2
	v_pk_mul_f32 v[6:7], v[24:25], v[24:25]
	v_add_f32_e32 v0, v1, v0
	v_add_f32_e32 v0, v6, v0
	v_pk_mul_f32 v[4:5], v[22:23], v[22:23]
	v_add_f32_e32 v0, v7, v0
	v_add_f32_e32 v0, v4, v0
	v_pk_mul_f32 v[10:11], v[28:29], v[28:29]
	v_add_f32_e32 v0, v5, v0
	v_add_f32_e32 v0, v10, v0
	v_pk_mul_f32 v[8:9], v[26:27], v[26:27]
	v_add_f32_e32 v0, v11, v0
	v_add_f32_e32 v0, v8, v0
	v_pk_mul_f32 v[34:35], v[20:21], v[20:21]
	v_add_f32_e32 v0, v9, v0
	v_add_f32_e32 v0, v34, v0
	v_pk_mul_f32 v[32:33], v[30:31], v[30:31]
	v_add_f32_e32 v0, v35, v0
	v_add_f32_e32 v0, v32, v0
	s_waitcnt vmcnt(3)
	v_lshlrev_b32_e32 v11, 16, v44
	v_and_b32_e32 v10, 0xffff0000, v44
	v_add_f32_e32 v34, v33, v0
	v_lshlrev_b32_e32 v3, 16, v42
	v_and_b32_e32 v2, 0xffff0000, v42
	v_and_b32_e32 v6, 0xffff0000, v45
	v_pk_mul_f32 v[0:1], v[10:11], v[10:11]
	v_lshlrev_b32_e32 v9, 16, v45
	v_and_b32_e32 v7, 0xffff0000, v43
	v_mov_b32_e32 v8, v6
	v_pk_fma_f32 v[0:1], v[2:3], v[2:3], v[0:1]
	v_lshlrev_b32_e32 v5, 16, v43
	v_mov_b32_e32 v4, v7
	v_pk_mul_f32 v[32:33], v[8:9], v[8:9]
	v_add_f32_e32 v1, v1, v34
	v_pk_fma_f32 v[32:33], v[4:5], v[4:5], v[32:33]
	v_add_f32_e32 v0, v0, v1
	v_add_f32_e32 v0, v33, v0
	v_add_f32_e32 v0, v32, v0
	v_mov_b32_e32 v1, v0
	s_nop 1
	v_permlane16_swap_b32_e32 v1, v0
	s_waitcnt lgkmcnt(0)
	v_add_f32_e32 v0, v0, v1
	v_mov_b32_e32 v1, v0
	s_nop 1
	v_permlane32_swap_b32_e32 v1, v0
	s_waitcnt lgkmcnt(0)
	v_add_f32_e32 v0, v0, v1
	v_fmamk_f32 v0, v0, 0x3c2aaaab, v128
	v_mul_f32_e32 v1, 0x4b800000, v0
	v_cmp_gt_f32_e32 vcc, s57, v0
	s_nop 1
	v_cndmask_b32_e32 v0, v0, v1, vcc
	v_rsq_f32_e32 v4, v0
	v_lshl_add_u64 v[0:1], s[36:37], 0, v[82:83]
	v_lshl_add_u64 v[0:1], v[0:1], 0, v[132:133]
	v_lshl_add_u64 v[126:127], v[0:1], 0, s[18:19]
	v_mul_f32_e32 v8, 0x45800000, v4
	v_cndmask_b32_e32 v4, v4, v8, vcc
	v_pk_mul_f32 v[12:13], v[12:13], v[4:5] op_sel_hi:[1,0]
	v_pk_mul_f32 v[14:15], v[14:15], v[4:5] op_sel_hi:[1,0]
	v_pk_mul_f32 v[10:11], v[4:5], v[10:11] op_sel_hi:[0,1]
	v_pk_mul_f32 v[2:3], v[4:5], v[2:3] op_sel_hi:[0,1]
	s_waitcnt vmcnt(0)
	v_pk_mul_f32 v[12:13], v[16:17], v[12:13]
	v_pk_mul_f32 v[14:15], v[18:19], v[14:15]
	v_cvt_pk_bf16_f32 v12, v12, v13
	v_cvt_pk_bf16_f32 v13, v14, v15
	global_store_dwordx2 v[0:1], v[12:13], off
	global_load_dwordx4 v[12:15], v[110:111], off offset:64
	v_pk_mul_f32 v[16:17], v[24:25], v[4:5] op_sel_hi:[1,0]
	v_pk_mul_f32 v[18:19], v[22:23], v[4:5] op_sel_hi:[1,0]
	s_waitcnt vmcnt(0)
	v_pk_mul_f32 v[12:13], v[12:13], v[16:17]
	v_pk_mul_f32 v[14:15], v[14:15], v[18:19]
	v_cvt_pk_bf16_f32 v12, v12, v13
	v_cvt_pk_bf16_f32 v13, v14, v15
	global_store_dwordx2 v[0:1], v[12:13], off offset:32
	global_load_dwordx4 v[12:15], v[110:111], off offset:128
	v_pk_mul_f32 v[16:17], v[28:29], v[4:5] op_sel_hi:[1,0]
	v_pk_mul_f32 v[18:19], v[26:27], v[4:5] op_sel_hi:[1,0]
	v_mul_f32_e32 v28, v4, v5
	v_mul_f32_e32 v29, v4, v9
	s_waitcnt vmcnt(0)
	v_pk_mul_f32 v[12:13], v[12:13], v[16:17]
	v_pk_mul_f32 v[14:15], v[14:15], v[18:19]
	v_cvt_pk_bf16_f32 v12, v12, v13
	v_cvt_pk_bf16_f32 v13, v14, v15
	global_store_dwordx2 v[0:1], v[12:13], off offset:64
	global_load_dwordx4 v[12:15], v[110:111], off offset:192
	v_pk_mul_f32 v[16:17], v[20:21], v[4:5] op_sel_hi:[1,0]
	v_pk_mul_f32 v[18:19], v[30:31], v[4:5] op_sel_hi:[1,0]
	v_pk_mul_f32 v[4:5], v[4:5], v[6:7] op_sel_hi:[0,1]
	s_waitcnt vmcnt(0)
	v_pk_mul_f32 v[12:13], v[12:13], v[16:17]
	v_pk_mul_f32 v[14:15], v[14:15], v[18:19]
	v_cvt_pk_bf16_f32 v12, v12, v13
	v_cvt_pk_bf16_f32 v13, v14, v15
	global_store_dwordx2 v[0:1], v[12:13], off offset:96
	global_load_dwordx4 v[12:15], v[110:111], off offset:320
	s_nop 0
	global_load_dwordx4 v[16:19], v[110:111], off offset:256
	global_load_dwordx4 v[20:23], v[80:81], off
	global_load_dwordx4 v[24:27], v[80:81], off offset:16
	s_waitcnt vmcnt(3)
	v_pk_mul_f32 v[6:7], v[10:11], v[12:13] op_sel:[1,0] op_sel_hi:[0,1]
	s_waitcnt vmcnt(2)
	v_mul_f32_e32 v10, v28, v18
	v_mov_b32_e32 v18, v15
	s_waitcnt vmcnt(1)
	v_mov_b32_e32 v8, v20
	v_mov_b32_e32 v9, v22
	v_mov_b32_e32 v22, v21
	v_pk_mul_f32 v[4:5], v[4:5], v[18:19]
	v_pk_mul_f32 v[2:3], v[2:3], v[16:17] op_sel:[1,0] op_sel_hi:[0,1]
	v_mul_f32_e32 v12, v29, v14
	s_waitcnt vmcnt(0)
	v_mov_b32_e32 v16, v25
	v_mov_b32_e32 v17, v27
	v_pk_mul_f32 v[20:21], v[22:23], v[6:7]
	v_pk_mul_f32 v[6:7], v[8:9], v[6:7]
	v_mov_b32_e32 v13, v4
	v_mov_b32_e32 v14, v24
	v_mov_b32_e32 v15, v26
	v_pk_fma_f32 v[8:9], v[8:9], v[2:3], v[20:21] neg_lo:[0,0,1] neg_hi:[0,0,1]
	v_pk_fma_f32 v[2:3], v[22:23], v[2:3], v[6:7]
	v_mov_b32_e32 v11, v5
	v_pk_mul_f32 v[4:5], v[26:27], v[4:5]
	v_pk_mul_f32 v[6:7], v[16:17], v[12:13]
	v_mul_f32_e32 v18, v24, v12
	v_mul_f32_e32 v24, v25, v10
	v_mov_b32_e32 v25, v5
	v_mov_b32_e32 v19, v4
	v_cvt_pk_bf16_f32 v4, v8, v9
	v_cvt_pk_bf16_f32 v8, v2, v3
	v_pk_fma_f32 v[2:3], v[14:15], v[10:11], v[6:7] neg_lo:[0,0,1] neg_hi:[0,0,1]
	v_pk_add_f32 v[134:135], v[24:25], v[18:19]
	v_cvt_pk_bf16_f32 v5, v2, v3
	global_store_dwordx2 v[0:1], v[4:5], off offset:128
	global_store_dword v[0:1], v8, off offset:160
	s_branch .LBB0_167

; DI f32x4 mfma16(bf16x8 a, bf16x8 b, f32x4 c) { return __builtin_amdgcn_mfma_f32_16x16x32_bf16(a, b, c, 0, 0, 0); }
; DI void gemm_block(f32x4 (&acc)[4][4], const u16* Ap, int lda, const u16* Bp, int ldb, int K, char* lds, int tid, bool swap_w1 = false) {
;   const int lane = tid & 63, q = lane >> 4, jn = lane & 15;
;   const int wave = __builtin_amdgcn_readfirstlane(tid >> 6), wa = wave >> 1, wb = wave & 1;
;   uint4 xa0, xa1, xa2, xa3, xb0, xb1, xb2, xb3;
;   uint4 ya0, ya1, ya2, ya3, yb0, yb1, yb2, yb3;
;   const int srow = tid >> 3, scol = tid & 7;
;   const unsigned voa = (unsigned)(srow * lda + scol * 8) * 2u, vob = (unsigned)(srow * ldb + scol * 8) * 2u;
;   const char* ag = reinterpret_cast<const char*>(Ap);
;   const char* bg = reinterpret_cast<const char*>(Bp);
;   char* st0 = lds + (srow * GROW + scol * 8) * 2;
;   const bool sw = swap_w1 && (wa == 1);
;   const char* a0p = sw ? (lds + G_TILE_BYTES + (wb * 64 + jn) * GROW * 2 + q * 16) : (lds + (wa * 64 + jn) * GROW * 2 + q * 16);
;   const char* b0p = sw ? (lds + (wa * 64 + jn) * GROW * 2 + q * 16) : (lds + G_TILE_BYTES + (wb * 64 + jn) * GROW * 2 + q * 16);
;     ...
;   auto compute = [&](int buf) {
; #pragma unroll
;     for (int ks = 0; ks < 2; ++ks) {
;       bf16x8 a[4], b[4];
; #pragma unroll
;       for (int i = 0; i < 4; ++i) a[i] = *reinterpret_cast<const bf16x8*>(a0p + buf * G_BUF_BYTES + i * 16 * GROW * 2 + ks * 64);
; #pragma unroll
;       for (int j = 0; j < 4; ++j) b[j] = *reinterpret_cast<const bf16x8*>(b0p + buf * G_BUF_BYTES + j * 16 * GROW * 2 + ks * 64);
;       __builtin_amdgcn_s_setprio(1);
; #pragma unroll
;       for (int i = 0; i < 4; ++i)
; #pragma unroll
;         for (int j = 0; j < 4; ++j) acc[i][j] = mfma16(a[i], b[j], acc[i][j]);
;       __builtin_amdgcn_s_setprio(0);
;     }
;   };
;   const int nkt = K >> 6;
;   GLOAD0(0);
;   GLOAD1(1);
;   GSTORE0(0);
;   __syncthreads();
;   for (int kt = 0; kt < nkt; kt += 2) {
;     if (kt + 2 < nkt) GLOAD0(kt + 2);
;     compute(0);
;     GSTORE1(1);
;     __syncthreads();
;     if (kt + 3 < nkt) GLOAD1(kt + 3);
;     compute(1);
;     if (kt + 2 < nkt) GSTORE0(0);
;     __syncthreads();
.LBB0_973:
	s_mov_b32 s20, s15
	s_lshl_b32 s0, s20, 7
	s_ashr_i32 s1, s0, 31
	s_lshl_b64 s[0:1], s[0:1], 9
	s_add_u32 s0, s57, s0
	s_addc_u32 s1, s58, s1
	v_lshl_add_u64 v[116:117], s[0:1], 0, v[50:51]
	v_add_co_u32_e32 v120, vcc, s42, v116
	global_load_dwordx4 v[2:5], v[116:117], off
	s_nop 0
	v_addc_co_u32_e32 v121, vcc, 0, v117, vcc
	v_add_co_u32_e32 v128, vcc, s43, v116
	global_load_dwordx4 v[6:9], v[120:121], off
	s_nop 0
	v_addc_co_u32_e32 v129, vcc, 0, v117, vcc
	global_load_dwordx4 v[10:13], v[128:129], off
	global_load_dwordx4 v[14:17], v[68:69], off offset:3408
	global_load_dwordx4 v[18:21], v[54:55], off
	global_load_dwordx4 v[22:25], v[56:57], off
	global_load_dwordx4 v[26:29], v[58:59], off
	v_add_co_u32_e32 v142, vcc, s28, v116
	v_readfirstlane_b32 s21, v144
	s_nop 0
	v_addc_co_u32_e32 v143, vcc, 0, v117, vcc
	global_load_dwordx4 v[30:33], v[142:143], off
	global_load_dwordx4 v[34:37], v[68:69], off offset:3536
	global_load_dwordx4 v[38:41], v[62:63], off
	global_load_dwordx4 v[42:45], v[64:65], off
	global_load_dwordx4 v[46:49], v[86:87], off
	global_load_dwordx4 v[102:105], v[116:117], off offset:128
	global_load_dwordx4 v[106:109], v[120:121], off offset:128
	global_load_dwordx4 v[110:113], v[128:129], off offset:128
	global_load_dwordx4 v[124:127], v[142:143], off offset:128
	s_lshr_b32 s0, s21, 1
	s_and_b32 s0, s0, 0xfffffc0
	v_or_b32_e32 v0, s0, v145
	v_mad_u64_u32 v[168:169], s[0:1], v0, s31, v[66:67]
	v_and_or_b32 v0, s21, 64, v145
	v_mad_u32_u24 v0, v0, s31, v66
	s_waitcnt vmcnt(12)
	ds_write_b128 v146, v[14:17] offset:18432
	s_waitcnt vmcnt(11)
	ds_write_b128 v146, v[18:21] offset:23040
	s_waitcnt vmcnt(10)
	ds_write_b128 v146, v[22:25] offset:27648
	s_waitcnt vmcnt(9)
	ds_write_b128 v146, v[26:29] offset:32256
	ds_write_b128 v146, v[2:5]
	ds_write_b128 v146, v[6:9] offset:4608
	ds_write_b128 v146, v[10:13] offset:9216
	s_waitcnt vmcnt(8)
	ds_write_b128 v146, v[30:33] offset:13824
	s_waitcnt lgkmcnt(0)
	s_barrier
	global_load_dwordx4 v[2:5], v[116:117], off offset:256
	global_load_dwordx4 v[6:9], v[120:121], off offset:256
	global_load_dwordx4 v[10:13], v[128:129], off offset:256
	global_load_dwordx4 v[14:17], v[142:143], off offset:256
	global_load_dwordx4 v[18:21], v[68:69], off offset:3664
	global_load_dwordx4 v[22:25], v[88:89], off
	global_load_dwordx4 v[26:29], v[90:91], off
	global_load_dwordx4 v[30:33], v[92:93], off
	ds_read_b128 v[134:137], v168
	ds_read_b128 v[138:141], v168 offset:2304
	ds_read_b128 v[152:155], v168 offset:4608
	ds_read_b128 v[156:159], v168 offset:6912
	ds_read_b128 v[162:165], v0 offset:18432
	ds_read_b128 v[172:175], v0 offset:20736
	ds_read_b128 v[176:179], v0 offset:23040
	ds_read_b128 v[180:183], v0 offset:25344
	s_setprio 1
	s_waitcnt lgkmcnt(3)
	v_mfma_f32_16x16x32_bf16 v[184:187], v[134:137], v[162:165], 0
	s_waitcnt lgkmcnt(2)
	v_mfma_f32_16x16x32_bf16 v[188:191], v[134:137], v[172:175], 0
	s_waitcnt lgkmcnt(1)
	v_mfma_f32_16x16x32_bf16 v[192:195], v[134:137], v[176:179], 0
	s_waitcnt lgkmcnt(0)
	v_mfma_f32_16x16x32_bf16 v[134:137], v[134:137], v[180:183], 0
	v_mfma_f32_16x16x32_bf16 v[196:199], v[138:141], v[162:165], 0
	v_mfma_f32_16x16x32_bf16 v[200:203], v[138:141], v[172:175], 0
	v_mfma_f32_16x16x32_bf16 v[204:207], v[138:141], v[176:179], 0
	v_mfma_f32_16x16x32_bf16 v[138:141], v[138:141], v[180:183], 0
	v_mfma_f32_16x16x32_bf16 v[208:211], v[152:155], v[162:165], 0
	v_mfma_f32_16x16x32_bf16 v[212:215], v[152:155], v[172:175], 0
	v_mfma_f32_16x16x32_bf16 v[216:219], v[152:155], v[176:179], 0
	v_mfma_f32_16x16x32_bf16 v[152:155], v[152:155], v[180:183], 0
	v_mfma_f32_16x16x32_bf16 v[162:165], v[156:159], v[162:165], 0
	v_mfma_f32_16x16x32_bf16 v[172:175], v[156:159], v[172:175], 0
	v_mfma_f32_16x16x32_bf16 v[176:179], v[156:159], v[176:179], 0
	v_mfma_f32_16x16x32_bf16 v[156:159], v[156:159], v[180:183], 0
	s_setprio 0
	ds_read_b128 v[180:183], v168 offset:64
	ds_read_b128 v[220:223], v168 offset:2368
	ds_read_b128 v[224:227], v168 offset:4672
	ds_read_b128 v[228:231], v168 offset:6976
	ds_read_b128 v[232:235], v0 offset:18496
	ds_read_b128 v[236:239], v0 offset:20800
	ds_read_b128 v[240:243], v0 offset:23104
	ds_read_b128 v[244:247], v0 offset:25408
	s_setprio 1
	s_waitcnt lgkmcnt(3)
	v_mfma_f32_16x16x32_bf16 v[184:187], v[180:183], v[232:235], v[184:187]
	s_waitcnt lgkmcnt(2)
	v_mfma_f32_16x16x32_bf16 v[188:191], v[180:183], v[236:239], v[188:191]
	s_waitcnt lgkmcnt(1)
	v_mfma_f32_16x16x32_bf16 v[192:195], v[180:183], v[240:243], v[192:195]
	s_waitcnt lgkmcnt(0)
	v_mfma_f32_16x16x32_bf16 v[134:137], v[180:183], v[244:247], v[134:137]
	v_mfma_f32_16x16x32_bf16 v[180:183], v[220:223], v[232:235], v[196:199]
	v_mfma_f32_16x16x32_bf16 v[196:199], v[220:223], v[236:239], v[200:203]
	v_mfma_f32_16x16x32_bf16 v[200:203], v[220:223], v[240:243], v[204:207]
	v_mfma_f32_16x16x32_bf16 v[138:141], v[220:223], v[244:247], v[138:141]
	v_mfma_f32_16x16x32_bf16 v[204:207], v[224:227], v[232:235], v[208:211]
	v_mfma_f32_16x16x32_bf16 v[208:211], v[224:227], v[236:239], v[212:215]
	v_mfma_f32_16x16x32_bf16 v[212:215], v[224:227], v[240:243], v[216:219]
	v_mfma_f32_16x16x32_bf16 v[152:155], v[224:227], v[244:247], v[152:155]
	v_mfma_f32_16x16x32_bf16 v[162:165], v[228:231], v[232:235], v[162:165]
	v_mfma_f32_16x16x32_bf16 v[172:175], v[228:231], v[236:239], v[172:175]
	v_mfma_f32_16x16x32_bf16 v[176:179], v[228:231], v[240:243], v[176:179]
	v_mfma_f32_16x16x32_bf16 v[156:159], v[228:231], v[244:247], v[156:159]
	s_setprio 0
	s_waitcnt vmcnt(11)
	ds_write_b128 v146, v[102:105] offset:36864
	s_waitcnt vmcnt(10)
	ds_write_b128 v146, v[106:109] offset:41472
	s_waitcnt vmcnt(9)
	ds_write_b128 v146, v[110:113] offset:46080
	s_waitcnt vmcnt(8)
	ds_write_b128 v146, v[124:127] offset:50688
	ds_write_b128 v146, v[34:37] offset:55296
	ds_write_b128 v146, v[38:41] offset:59904
	ds_write_b128 v146, v[42:45] offset:64512
	ds_write_b128 v147, v[46:49]
	s_waitcnt lgkmcnt(0)
	s_barrier
; DI f32x4 mfma16(bf16x8 a, bf16x8 b, f32x4 c) { return __builtin_amdgcn_mfma_f32_16x16x32_bf16(a, b, c, 0, 0, 0); }
; #define GLOAD0(kt) { GL(xa0, ag, lda, voa, 0, kt); GL(xa1, ag, lda, voa, 1, kt); GL(xa2, ag, lda, voa, 2, kt); GL(xa3, ag, lda, voa, 3, kt); GL(xb0, bg, ldb, vob, 0, kt); GL(xb1, bg, ldb, vob, 1, kt); GL(xb2, bg, ldb, vob, 2, kt); GL(xb3, bg, ldb, vob, 3, kt); }
; #define GLOAD1(kt) { GL(ya0, ag, lda, voa, 0, kt); GL(ya1, ag, lda, voa, 1, kt); GL(ya2, ag, lda, voa, 2, kt); GL(ya3, ag, lda, voa, 3, kt); GL(yb0, bg, ldb, vob, 0, kt); GL(yb1, bg, ldb, vob, 1, kt); GL(yb2, bg, ldb, vob, 2, kt); GL(yb3, bg, ldb, vob, 3, kt); }
; DI void gemm_block(f32x4 (&acc)[4][4], const u16* Ap, int lda, const u16* Bp, int ldb, int K, char* lds, int tid, bool swap_w1 = false) {
;     ...
;   auto compute = [&](int buf) {
; #pragma unroll
;     for (int ks = 0; ks < 2; ++ks) {
;       bf16x8 a[4], b[4];
; #pragma unroll
;       for (int i = 0; i < 4; ++i) a[i] = *reinterpret_cast<const bf16x8*>(a0p + buf * G_BUF_BYTES + i * 16 * GROW * 2 + ks * 64);
; #pragma unroll
;       for (int j = 0; j < 4; ++j) b[j] = *reinterpret_cast<const bf16x8*>(b0p + buf * G_BUF_BYTES + j * 16 * GROW * 2 + ks * 64);
;       __builtin_amdgcn_s_setprio(1);
; #pragma unroll
;       for (int i = 0; i < 4; ++i)
; #pragma unroll
;         for (int j = 0; j < 4; ++j) acc[i][j] = mfma16(a[i], b[j], acc[i][j]);
;       __builtin_amdgcn_s_setprio(0);
;     }
;   };
;   const int nkt = K >> 6;
;   GLOAD0(0);
;   GLOAD1(1);
;   GSTORE0(0);
;   __syncthreads();
;   for (int kt = 0; kt < nkt; kt += 2) {
;     if (kt + 2 < nkt) GLOAD0(kt + 2);
;     compute(0);
;     GSTORE1(1);
;     __syncthreads();
;     if (kt + 3 < nkt) GLOAD1(kt + 3);
;     compute(1);
;     if (kt + 2 < nkt) GSTORE0(0);
;     __syncthreads();
	global_load_dwordx4 v[34:37], v[116:117], off offset:384
	global_load_dwordx4 v[38:41], v[120:121], off offset:384
	global_load_dwordx4 v[42:45], v[128:129], off offset:384
	global_load_dwordx4 v[46:49], v[142:143], off offset:384
	global_load_dwordx4 v[102:105], v[68:69], off offset:3792
	global_load_dwordx4 v[106:109], v[94:95], off
	global_load_dwordx4 v[110:113], v[96:97], off
	global_load_dwordx4 v[124:127], v[98:99], off
	ds_read_b128 v[216:219], v168 offset:36864
	ds_read_b128 v[220:223], v168 offset:39168
	ds_read_b128 v[224:227], v168 offset:41472
	ds_read_b128 v[228:231], v168 offset:43776
	ds_read_b128 v[232:235], v0 offset:55296
	ds_read_b128 v[236:239], v0 offset:57600
	ds_read_b128 v[240:243], v0 offset:59904
	ds_read_b128 v[244:247], v0 offset:62208
	s_setprio 1
	s_waitcnt lgkmcnt(3)
	v_mfma_f32_16x16x32_bf16 v[184:187], v[216:219], v[232:235], v[184:187]
	s_waitcnt lgkmcnt(2)
	v_mfma_f32_16x16x32_bf16 v[188:191], v[216:219], v[236:239], v[188:191]
	s_waitcnt lgkmcnt(1)
	v_mfma_f32_16x16x32_bf16 v[192:195], v[216:219], v[240:243], v[192:195]
	s_waitcnt lgkmcnt(0)
	v_mfma_f32_16x16x32_bf16 v[134:137], v[216:219], v[244:247], v[134:137]
	v_mfma_f32_16x16x32_bf16 v[180:183], v[220:223], v[232:235], v[180:183]
	v_mfma_f32_16x16x32_bf16 v[196:199], v[220:223], v[236:239], v[196:199]
	v_mfma_f32_16x16x32_bf16 v[200:203], v[220:223], v[240:243], v[200:203]
	v_mfma_f32_16x16x32_bf16 v[138:141], v[220:223], v[244:247], v[138:141]
	v_mfma_f32_16x16x32_bf16 v[204:207], v[224:227], v[232:235], v[204:207]
	v_mfma_f32_16x16x32_bf16 v[208:211], v[224:227], v[236:239], v[208:211]
	v_mfma_f32_16x16x32_bf16 v[212:215], v[224:227], v[240:243], v[212:215]
	v_mfma_f32_16x16x32_bf16 v[152:155], v[224:227], v[244:247], v[152:155]
	v_mfma_f32_16x16x32_bf16 v[162:165], v[228:231], v[232:235], v[162:165]
	v_mfma_f32_16x16x32_bf16 v[172:175], v[228:231], v[236:239], v[172:175]
	v_mfma_f32_16x16x32_bf16 v[176:179], v[228:231], v[240:243], v[176:179]
	v_mfma_f32_16x16x32_bf16 v[156:159], v[228:231], v[244:247], v[156:159]
	s_setprio 0
	ds_read_b128 v[216:219], v168 offset:36928
	ds_read_b128 v[220:223], v168 offset:39232
	ds_read_b128 v[224:227], v168 offset:41536
	ds_read_b128 v[228:231], v168 offset:43840
	ds_read_b128 v[232:235], v0 offset:55360
	ds_read_b128 v[236:239], v0 offset:57664
	ds_read_b128 v[240:243], v0 offset:59968
	ds_read_b128 v[244:247], v0 offset:62272
	s_setprio 1
	s_waitcnt lgkmcnt(3)
	v_mfma_f32_16x16x32_bf16 v[184:187], v[216:219], v[232:235], v[184:187]
	s_waitcnt lgkmcnt(2)
	v_mfma_f32_16x16x32_bf16 v[188:191], v[216:219], v[236:239], v[188:191]
	s_waitcnt lgkmcnt(1)
	v_mfma_f32_16x16x32_bf16 v[192:195], v[216:219], v[240:243], v[192:195]
	s_waitcnt lgkmcnt(0)
	v_mfma_f32_16x16x32_bf16 v[134:137], v[216:219], v[244:247], v[134:137]
	v_mfma_f32_16x16x32_bf16 v[180:183], v[220:223], v[232:235], v[180:183]
	v_mfma_f32_16x16x32_bf16 v[196:199], v[220:223], v[236:239], v[196:199]
	v_mfma_f32_16x16x32_bf16 v[200:203], v[220:223], v[240:243], v[200:203]
	v_mfma_f32_16x16x32_bf16 v[138:141], v[220:223], v[244:247], v[138:141]
	v_mfma_f32_16x16x32_bf16 v[204:207], v[224:227], v[232:235], v[204:207]
	v_mfma_f32_16x16x32_bf16 v[208:211], v[224:227], v[236:239], v[208:211]
	v_mfma_f32_16x16x32_bf16 v[212:215], v[224:227], v[240:243], v[212:215]
	v_mfma_f32_16x16x32_bf16 v[152:155], v[224:227], v[244:247], v[152:155]
	v_mfma_f32_16x16x32_bf16 v[162:165], v[228:231], v[232:235], v[162:165]
	v_mfma_f32_16x16x32_bf16 v[172:175], v[228:231], v[236:239], v[172:175]
	v_mfma_f32_16x16x32_bf16 v[176:179], v[228:231], v[240:243], v[176:179]
	v_mfma_f32_16x16x32_bf16 v[156:159], v[228:231], v[244:247], v[156:159]
	s_setprio 0
	s_waitcnt vmcnt(15)
	ds_write_b128 v146, v[2:5]
	s_waitcnt vmcnt(14)
	ds_write_b128 v146, v[6:9] offset:4608
	s_waitcnt vmcnt(13)
	ds_write_b128 v146, v[10:13] offset:9216
	s_waitcnt vmcnt(12)
	ds_write_b128 v146, v[14:17] offset:13824
	s_waitcnt vmcnt(11)
	ds_write_b128 v146, v[18:21] offset:18432
	s_waitcnt vmcnt(10)
	ds_write_b128 v146, v[22:25] offset:23040
	s_waitcnt vmcnt(9)
	ds_write_b128 v146, v[26:29] offset:27648
	s_waitcnt vmcnt(8)
	ds_write_b128 v146, v[30:33] offset:32256
	s_waitcnt lgkmcnt(0)
	s_barrier
	ds_read_b128 v[2:5], v168
	ds_read_b128 v[6:9], v168 offset:2304
	ds_read_b128 v[10:13], v168 offset:4608
	ds_read_b128 v[14:17], v168 offset:6912
	ds_read_b128 v[18:21], v0 offset:18432
	ds_read_b128 v[22:25], v0 offset:20736
	ds_read_b128 v[26:29], v0 offset:23040
	ds_read_b128 v[30:33], v0 offset:25344
	s_setprio 1
	s_waitcnt lgkmcnt(3)
	v_mfma_f32_16x16x32_bf16 v[184:187], v[2:5], v[18:21], v[184:187]
	s_waitcnt lgkmcnt(2)
	v_mfma_f32_16x16x32_bf16 v[188:191], v[2:5], v[22:25], v[188:191]
	s_waitcnt lgkmcnt(1)
	v_mfma_f32_16x16x32_bf16 v[192:195], v[2:5], v[26:29], v[192:195]
	s_waitcnt lgkmcnt(0)
	v_mfma_f32_16x16x32_bf16 v[2:5], v[2:5], v[30:33], v[134:137]
	v_mfma_f32_16x16x32_bf16 v[134:137], v[6:9], v[18:21], v[180:183]
	v_mfma_f32_16x16x32_bf16 v[180:183], v[6:9], v[22:25], v[196:199]
	v_mfma_f32_16x16x32_bf16 v[196:199], v[6:9], v[26:29], v[200:203]
	v_mfma_f32_16x16x32_bf16 v[6:9], v[6:9], v[30:33], v[138:141]
	v_mfma_f32_16x16x32_bf16 v[138:141], v[10:13], v[18:21], v[204:207]
	v_mfma_f32_16x16x32_bf16 v[200:203], v[10:13], v[22:25], v[208:211]
	v_mfma_f32_16x16x32_bf16 v[204:207], v[10:13], v[26:29], v[212:215]
	v_mfma_f32_16x16x32_bf16 v[10:13], v[10:13], v[30:33], v[152:155]
	v_mfma_f32_16x16x32_bf16 v[18:21], v[14:17], v[18:21], v[162:165]
	v_mfma_f32_16x16x32_bf16 v[22:25], v[14:17], v[22:25], v[172:175]
	v_mfma_f32_16x16x32_bf16 v[26:29], v[14:17], v[26:29], v[176:179]
	v_mfma_f32_16x16x32_bf16 v[14:17], v[14:17], v[30:33], v[156:159]
	s_setprio 0
	ds_read_b128 v[30:33], v168 offset:64
	ds_read_b128 v[152:155], v168 offset:2368
	ds_read_b128 v[156:159], v168 offset:4672
	ds_read_b128 v[162:165], v168 offset:6976
	ds_read_b128 v[172:175], v0 offset:18496
	ds_read_b128 v[176:179], v0 offset:20800
	ds_read_b128 v[208:211], v0 offset:23104
	ds_read_b128 v[212:215], v0 offset:25408
	s_setprio 1
	s_waitcnt lgkmcnt(3)
; DI f32x4 mfma16(bf16x8 a, bf16x8 b, f32x4 c) { return __builtin_amdgcn_mfma_f32_16x16x32_bf16(a, b, c, 0, 0, 0); }
; DI float red4(float v) { v += __shfl_xor(v, 16); v += __shfl_xor(v, 32); return v; }
; #define GLOAD0(kt) { GL(xa0, ag, lda, voa, 0, kt); GL(xa1, ag, lda, voa, 1, kt); GL(xa2, ag, lda, voa, 2, kt); GL(xa3, ag, lda, voa, 3, kt); GL(xb0, bg, ldb, vob, 0, kt); GL(xb1, bg, ldb, vob, 1, kt); GL(xb2, bg, ldb, vob, 2, kt); GL(xb3, bg, ldb, vob, 3, kt); }
; #define GLOAD1(kt) { GL(ya0, ag, lda, voa, 0, kt); GL(ya1, ag, lda, voa, 1, kt); GL(ya2, ag, lda, voa, 2, kt); GL(ya3, ag, lda, voa, 3, kt); GL(yb0, bg, ldb, vob, 0, kt); GL(yb1, bg, ldb, vob, 1, kt); GL(yb2, bg, ldb, vob, 2, kt); GL(yb3, bg, ldb, vob, 3, kt); }
; DI void gemm_block(f32x4 (&acc)[4][4], const u16* Ap, int lda, const u16* Bp, int ldb, int K, char* lds, int tid, bool swap_w1 = false) {
;     ...
;   auto compute = [&](int buf) {
; #pragma unroll
;     for (int ks = 0; ks < 2; ++ks) {
;       bf16x8 a[4], b[4];
; #pragma unroll
;       for (int i = 0; i < 4; ++i) a[i] = *reinterpret_cast<const bf16x8*>(a0p + buf * G_BUF_BYTES + i * 16 * GROW * 2 + ks * 64);
; #pragma unroll
;       for (int j = 0; j < 4; ++j) b[j] = *reinterpret_cast<const bf16x8*>(b0p + buf * G_BUF_BYTES + j * 16 * GROW * 2 + ks * 64);
;       __builtin_amdgcn_s_setprio(1);
; #pragma unroll
;       for (int i = 0; i < 4; ++i)
; #pragma unroll
;         for (int j = 0; j < 4; ++j) acc[i][j] = mfma16(a[i], b[j], acc[i][j]);
;       __builtin_amdgcn_s_setprio(0);
;     }
;   };
;   const int nkt = K >> 6;
;   GLOAD0(0);
;   GLOAD1(1);
;   GSTORE0(0);
;   __syncthreads();
;   for (int kt = 0; kt < nkt; kt += 2) {
;     if (kt + 2 < nkt) GLOAD0(kt + 2);
;     compute(0);
;     GSTORE1(1);
;     __syncthreads();
;     if (kt + 3 < nkt) GLOAD1(kt + 3);
;     compute(1);
;     if (kt + 2 < nkt) GSTORE0(0);
;     __syncthreads();
; DI void prep_mla_tile(const Params& P, int l, int tt, char* lds, float* s_r, float* s_ss) {
;     ...
; #pragma unroll
;     for (int j = 0; j < 4; ++j) {
;       const int tl = wb * 64 + 16 * j + jn; const float rq = s_r[tl];
;       float ss = 0.f;
; #pragma unroll
;       for (int i = 0; i < 4; ++i)
; #pragma unroll
;         for (int r = 0; r < 4; ++r) { const float v = acc[i][j][r] * rq; acc[i][j][r] = v; ss += v * v; }
;       ss = red4(ss);
;       if (q == 0) s_ss[wa * 128 + tl] = ss;
;     }
	v_mfma_f32_16x16x32_bf16 v[184:187], v[30:33], v[172:175], v[184:187]
	s_waitcnt lgkmcnt(2)
	v_mfma_f32_16x16x32_bf16 v[188:191], v[30:33], v[176:179], v[188:191]
	s_waitcnt lgkmcnt(1)
	v_mfma_f32_16x16x32_bf16 v[192:195], v[30:33], v[208:211], v[192:195]
	s_waitcnt lgkmcnt(0)
	v_mfma_f32_16x16x32_bf16 v[2:5], v[30:33], v[212:215], v[2:5]
	v_mfma_f32_16x16x32_bf16 v[30:33], v[152:155], v[172:175], v[134:137]
	v_mfma_f32_16x16x32_bf16 v[6:9], v[152:155], v[212:215], v[6:9]
	v_mfma_f32_16x16x32_bf16 v[10:13], v[156:159], v[212:215], v[10:13]
	v_mfma_f32_16x16x32_bf16 v[18:21], v[162:165], v[172:175], v[18:21]
	v_mfma_f32_16x16x32_bf16 v[22:25], v[162:165], v[176:179], v[22:25]
	v_mfma_f32_16x16x32_bf16 v[26:29], v[162:165], v[208:211], v[26:29]
	v_mfma_f32_16x16x32_bf16 v[14:17], v[162:165], v[212:215], v[14:17]
	v_mfma_f32_16x16x32_bf16 v[134:137], v[152:155], v[176:179], v[180:183]
	v_mfma_f32_16x16x32_bf16 v[180:183], v[152:155], v[208:211], v[196:199]
	v_mfma_f32_16x16x32_bf16 v[138:141], v[156:159], v[172:175], v[138:141]
	v_mfma_f32_16x16x32_bf16 v[152:155], v[156:159], v[176:179], v[200:203]
	v_mfma_f32_16x16x32_bf16 v[196:199], v[156:159], v[208:211], v[204:207]
	s_setprio 0
	s_waitcnt vmcnt(7)
	ds_write_b128 v146, v[34:37] offset:36864
	s_waitcnt vmcnt(6)
	ds_write_b128 v146, v[38:41] offset:41472
	s_waitcnt vmcnt(5)
	ds_write_b128 v146, v[42:45] offset:46080
	s_waitcnt vmcnt(4)
	ds_write_b128 v146, v[46:49] offset:50688
	s_waitcnt vmcnt(3)
	ds_write_b128 v146, v[102:105] offset:55296
	s_waitcnt vmcnt(2)
	ds_write_b128 v146, v[106:109] offset:59904
	s_waitcnt vmcnt(1)
	ds_write_b128 v146, v[110:113] offset:64512
	s_waitcnt vmcnt(0)
	ds_write_b128 v147, v[124:127]
	s_waitcnt lgkmcnt(0)
	s_barrier
	ds_read_b128 v[34:37], v168 offset:36864
	ds_read_b128 v[38:41], v168 offset:39168
	ds_read_b128 v[42:45], v168 offset:41472
	ds_read_b128 v[46:49], v168 offset:43776
	ds_read_b128 v[102:105], v0 offset:55296
	ds_read_b128 v[106:109], v0 offset:57600
	ds_read_b128 v[110:113], v0 offset:59904
	ds_read_b128 v[124:127], v0 offset:62208
	s_setprio 1
	s_waitcnt lgkmcnt(3)
	v_mfma_f32_16x16x32_bf16 v[156:159], v[34:37], v[102:105], v[184:187]
	s_waitcnt lgkmcnt(2)
	v_mfma_f32_16x16x32_bf16 v[162:165], v[34:37], v[106:109], v[188:191]
	s_waitcnt lgkmcnt(1)
	v_mfma_f32_16x16x32_bf16 v[172:175], v[34:37], v[110:113], v[192:195]
	s_waitcnt lgkmcnt(0)
	v_mfma_f32_16x16x32_bf16 v[2:5], v[34:37], v[124:127], v[2:5]
	v_mfma_f32_16x16x32_bf16 v[30:33], v[38:41], v[102:105], v[30:33]
	v_mfma_f32_16x16x32_bf16 v[34:37], v[38:41], v[106:109], v[134:137]
	v_mfma_f32_16x16x32_bf16 v[134:137], v[38:41], v[110:113], v[180:183]
	v_mfma_f32_16x16x32_bf16 v[6:9], v[38:41], v[124:127], v[6:9]
	v_mfma_f32_16x16x32_bf16 v[38:41], v[42:45], v[102:105], v[138:141]
	v_mfma_f32_16x16x32_bf16 v[138:141], v[42:45], v[106:109], v[152:155]
	v_mfma_f32_16x16x32_bf16 v[152:155], v[42:45], v[110:113], v[196:199]
	v_mfma_f32_16x16x32_bf16 v[18:21], v[46:49], v[102:105], v[18:21]
	v_mfma_f32_16x16x32_bf16 v[102:105], v[46:49], v[106:109], v[22:25]
	v_mfma_f32_16x16x32_bf16 v[106:109], v[46:49], v[110:113], v[26:29]
	v_mfma_f32_16x16x32_bf16 v[110:113], v[46:49], v[124:127], v[14:17]
	v_mfma_f32_16x16x32_bf16 v[176:179], v[42:45], v[124:127], v[10:13]
	s_setprio 0
	s_nop 1
	ds_read_b128 v[10:13], v168 offset:36928
	ds_read_b128 v[14:17], v168 offset:39232
	ds_read_b128 v[124:127], v168 offset:41536
	ds_read_b128 v[180:183], v168 offset:43840
	ds_read_b128 v[184:187], v0 offset:55360
	ds_read_b128 v[188:191], v0 offset:57664
	ds_read_b128 v[192:195], v0 offset:59968
	ds_read_b128 v[196:199], v0 offset:62272
	s_setprio 1
	s_waitcnt lgkmcnt(3)
	v_mfma_f32_16x16x32_bf16 v[156:159], v[10:13], v[184:187], v[156:159]
	s_waitcnt lgkmcnt(2)
	v_mfma_f32_16x16x32_bf16 v[42:45], v[10:13], v[188:191], v[162:165]
	s_waitcnt lgkmcnt(1)
	v_mfma_f32_16x16x32_bf16 v[26:29], v[10:13], v[192:195], v[172:175]
	s_waitcnt lgkmcnt(0)
	v_mfma_f32_16x16x32_bf16 v[10:13], v[10:13], v[196:199], v[2:5]
	v_mfma_f32_16x16x32_bf16 v[162:165], v[14:17], v[184:187], v[30:33]
	v_mfma_f32_16x16x32_bf16 v[46:49], v[14:17], v[188:191], v[34:37]
	v_mfma_f32_16x16x32_bf16 v[30:33], v[14:17], v[192:195], v[134:137]
	v_mfma_f32_16x16x32_bf16 v[14:17], v[14:17], v[196:199], v[6:9]
	v_mfma_f32_16x16x32_bf16 v[134:137], v[124:127], v[184:187], v[38:41]
	v_mfma_f32_16x16x32_bf16 v[38:41], v[124:127], v[188:191], v[138:141]
	v_mfma_f32_16x16x32_bf16 v[22:25], v[124:127], v[192:195], v[152:155]
	v_mfma_f32_16x16x32_bf16 v[6:9], v[124:127], v[196:199], v[176:179]
	v_mfma_f32_16x16x32_bf16 v[138:141], v[180:183], v[184:187], v[18:21]
	v_mfma_f32_16x16x32_bf16 v[34:37], v[180:183], v[188:191], v[102:105]
	v_mfma_f32_16x16x32_bf16 v[18:21], v[180:183], v[192:195], v[106:109]
	v_mfma_f32_16x16x32_bf16 v[2:5], v[180:183], v[196:199], v[110:113]
	s_setprio 0
	s_barrier
	ds_read_b32 v102, v150
	s_waitcnt lgkmcnt(0)
	v_mul_f32_e32 v0, v157, v102
	v_mul_f32_e32 v117, v156, v102
	v_mul_f32_e32 v67, v0, v0
	v_mul_f32_e32 v126, v158, v102
	v_mov_b32_e32 v158, v165
	v_fmac_f32_e32 v67, v117, v117
	v_pk_mul_f32 v[120:121], v[158:159], v[102:103] op_sel_hi:[1,0]
	v_fmac_f32_e32 v67, v126, v126
	v_pk_mul_f32 v[124:125], v[162:163], v[102:103] op_sel_hi:[1,0]
	v_pk_mul_f32 v[106:107], v[120:121], v[120:121]
	v_pk_mul_f32 v[104:105], v[124:125], v[124:125]
	v_add_f32_e32 v67, v107, v67
	v_add_f32_e32 v67, v104, v67
	v_mul_f32_e32 v116, v164, v102
	v_add_f32_e32 v67, v105, v67
	v_fmac_f32_e32 v67, v116, v116
	v_pk_mul_f32 v[112:113], v[134:135], v[102:103] op_sel_hi:[1,0]
	v_add_f32_e32 v67, v106, v67
	v_pk_mul_f32 v[104:105], v[112:113], v[112:113]
	v_pk_mul_f32 v[110:111], v[136:137], v[102:103] op_sel_hi:[1,0]
	v_add_f32_e32 v67, v104, v67
	v_add_f32_e32 v67, v105, v67
	v_pk_mul_f32 v[104:105], v[110:111], v[110:111]
	v_pk_mul_f32 v[108:109], v[138:139], v[102:103] op_sel_hi:[1,0]
	v_add_f32_e32 v67, v104, v67
	v_add_f32_e32 v67, v105, v67
	v_pk_mul_f32 v[104:105], v[108:109], v[108:109]
	v_pk_mul_f32 v[106:107], v[140:141], v[102:103] op_sel_hi:[1,0]
	v_add_f32_e32 v67, v104, v67
	v_add_f32_e32 v67, v105, v67
	v_pk_mul_f32 v[102:103], v[106:107], v[106:107]
	s_nop 0
	v_add_f32_e32 v67, v102, v67
	v_add_f32_e32 v67, v103, v67
	v_mov_b32_e32 v102, v67
	s_nop 1
	v_permlane16_swap_b32_e32 v102, v67
	s_waitcnt lgkmcnt(0)
	v_add_f32_e32 v67, v67, v102
	v_mov_b32_e32 v102, v67
	s_nop 1
	v_permlane32_swap_b32_e32 v102, v67
	s_and_saveexec_b64 s[0:1], s[2:3]
	s_cbranch_execz .LBB0_975
	s_waitcnt lgkmcnt(0)
	v_add_f32_e32 v67, v67, v102
	ds_write_b32 v115, v67 offset:1024
; DI float red4(float v) { v += __shfl_xor(v, 16); v += __shfl_xor(v, 32); return v; }
; DI void prep_mla_tile(const Params& P, int l, int tt, char* lds, float* s_r, float* s_ss) {
;     ...
; #pragma unroll
;     for (int j = 0; j < 4; ++j) {
;       const int tl = wb * 64 + 16 * j + jn; const float rq = s_r[tl];
;       float ss = 0.f;
; #pragma unroll
;       for (int i = 0; i < 4; ++i)
; #pragma unroll
;         for (int r = 0; r < 4; ++r) { const float v = acc[i][j][r] * rq; acc[i][j][r] = v; ss += v * v; }
;       ss = red4(ss);
;       if (q == 0) s_ss[wa * 128 + tl] = ss;
;     }
.LBB0_975:
	s_or_b64 exec, exec, s[0:1]
	ds_read_b32 v128, v150 offset:64
	s_waitcnt lgkmcnt(0)
	v_mul_f32_e32 v105, v43, v128
	v_mul_f32_e32 v123, v42, v128
	v_mul_f32_e32 v104, v44, v128
	v_pk_mul_f32 v[102:103], v[46:47], v[128:129] op_sel_hi:[1,0]
	v_mul_f32_e32 v47, v105, v105
	v_mov_b32_e32 v44, v49
	v_fmac_f32_e32 v47, v123, v123
	v_mul_f32_e32 v46, v48, v128
	v_pk_mul_f32 v[48:49], v[44:45], v[128:129] op_sel_hi:[1,0]
	v_fmac_f32_e32 v47, v104, v104
	v_pk_mul_f32 v[44:45], v[48:49], v[48:49]
	v_pk_mul_f32 v[42:43], v[102:103], v[102:103]
	v_add_f32_e32 v45, v45, v47
	v_add_f32_e32 v42, v42, v45
	v_add_f32_e32 v42, v43, v42
	v_fmac_f32_e32 v42, v46, v46
	v_add_f32_e32 v42, v44, v42
	v_pk_mul_f32 v[44:45], v[38:39], v[128:129] op_sel_hi:[1,0]
	s_nop 0
	v_pk_mul_f32 v[38:39], v[44:45], v[44:45]
	s_nop 0
	v_add_f32_e32 v38, v38, v42
	v_pk_mul_f32 v[42:43], v[40:41], v[128:129] op_sel_hi:[1,0]
	v_add_f32_e32 v47, v39, v38
	v_pk_mul_f32 v[38:39], v[42:43], v[42:43]
	v_pk_mul_f32 v[40:41], v[34:35], v[128:129] op_sel_hi:[1,0]
	v_add_f32_e32 v38, v38, v47
	v_add_f32_e32 v38, v39, v38
	v_pk_mul_f32 v[34:35], v[40:41], v[40:41]
	s_nop 0
	v_add_f32_e32 v34, v34, v38
	v_pk_mul_f32 v[38:39], v[36:37], v[128:129] op_sel_hi:[1,0]
	v_add_f32_e32 v47, v35, v34
	v_pk_mul_f32 v[34:35], v[38:39], v[38:39]
	s_nop 0
	v_add_f32_e32 v34, v34, v47
	v_add_f32_e32 v34, v35, v34
	v_mov_b32_e32 v35, v34
	s_nop 1
	v_permlane16_swap_b32_e32 v35, v34
	s_waitcnt lgkmcnt(0)
	v_add_f32_e32 v34, v34, v35
	v_mov_b32_e32 v35, v34
	s_nop 1
	v_permlane32_swap_b32_e32 v35, v34
	s_and_saveexec_b64 s[0:1], s[2:3]
	s_cbranch_execz .LBB0_977
	s_waitcnt lgkmcnt(0)
	v_add_f32_e32 v34, v34, v35
	ds_write_b32 v115, v34 offset:1088
.LBB0_977:
	s_or_b64 exec, exec, s[0:1]
	ds_read_b32 v128, v150 offset:128
	s_waitcnt lgkmcnt(0)
	v_mul_f32_e32 v37, v27, v128
	v_mul_f32_e32 v119, v26, v128
	v_mul_f32_e32 v36, v28, v128
	v_pk_mul_f32 v[34:35], v[30:31], v[128:129] op_sel_hi:[1,0]
	v_mul_f32_e32 v31, v37, v37
	v_mov_b32_e32 v28, v33
	v_fmac_f32_e32 v31, v119, v119
	v_mul_f32_e32 v30, v32, v128
	v_pk_mul_f32 v[32:33], v[28:29], v[128:129] op_sel_hi:[1,0]
	v_fmac_f32_e32 v31, v36, v36
	v_pk_mul_f32 v[28:29], v[32:33], v[32:33]
	v_pk_mul_f32 v[26:27], v[34:35], v[34:35]
	v_add_f32_e32 v29, v29, v31
	v_add_f32_e32 v26, v26, v29
	v_add_f32_e32 v26, v27, v26
	v_fmac_f32_e32 v26, v30, v30
	v_add_f32_e32 v26, v28, v26
	v_pk_mul_f32 v[28:29], v[22:23], v[128:129] op_sel_hi:[1,0]
	s_nop 0
	v_pk_mul_f32 v[22:23], v[28:29], v[28:29]
	s_nop 0
	v_add_f32_e32 v22, v22, v26
	v_pk_mul_f32 v[26:27], v[24:25], v[128:129] op_sel_hi:[1,0]
	v_add_f32_e32 v31, v23, v22
	v_pk_mul_f32 v[22:23], v[26:27], v[26:27]
	v_pk_mul_f32 v[24:25], v[18:19], v[128:129] op_sel_hi:[1,0]
	v_add_f32_e32 v22, v22, v31
	v_add_f32_e32 v22, v23, v22
	v_pk_mul_f32 v[18:19], v[24:25], v[24:25]
	s_nop 0
	v_add_f32_e32 v18, v18, v22
	v_pk_mul_f32 v[22:23], v[20:21], v[128:129] op_sel_hi:[1,0]
	v_add_f32_e32 v31, v19, v18
	v_pk_mul_f32 v[18:19], v[22:23], v[22:23]
	s_nop 0
	v_add_f32_e32 v18, v18, v31
	v_add_f32_e32 v18, v19, v18
	v_mov_b32_e32 v19, v18
	s_nop 1
	v_permlane16_swap_b32_e32 v19, v18
	s_waitcnt lgkmcnt(0)
	v_add_f32_e32 v18, v18, v19
	v_mov_b32_e32 v19, v18
	s_nop 1
	v_permlane32_swap_b32_e32 v19, v18
	s_and_saveexec_b64 s[0:1], s[2:3]
	s_cbranch_execz .LBB0_979
	s_waitcnt lgkmcnt(0)
	v_add_f32_e32 v18, v18, v19
	ds_write_b32 v115, v18 offset:1152
.LBB0_979:
	s_or_b64 exec, exec, s[0:1]
	ds_read_b32 v128, v150 offset:192
	s_waitcnt lgkmcnt(0)
	v_mul_f32_e32 v21, v11, v128
	v_mul_f32_e32 v67, v10, v128
	v_mul_f32_e32 v20, v12, v128
	v_pk_mul_f32 v[18:19], v[14:15], v[128:129] op_sel_hi:[1,0]
	v_mul_f32_e32 v15, v21, v21
	v_mov_b32_e32 v12, v17
	v_fmac_f32_e32 v15, v67, v67
	v_pk_mul_f32 v[12:13], v[12:13], v[128:129] op_sel_hi:[1,0]
	v_fmac_f32_e32 v15, v20, v20
	v_mul_f32_e32 v14, v16, v128
	v_pk_mul_f32 v[16:17], v[12:13], v[12:13]
	v_pk_mul_f32 v[10:11], v[18:19], v[18:19]
	v_add_f32_e32 v15, v17, v15
	v_add_f32_e32 v10, v10, v15
	v_add_f32_e32 v10, v11, v10
	v_fmac_f32_e32 v10, v14, v14
	v_add_f32_e32 v15, v16, v10
	v_pk_mul_f32 v[10:11], v[6:7], v[128:129] op_sel_hi:[1,0]
	v_pk_mul_f32 v[8:9], v[8:9], v[128:129] op_sel_hi:[1,0]
	v_pk_mul_f32 v[6:7], v[10:11], v[10:11]
	s_nop 0
	v_add_f32_e32 v6, v6, v15
	v_add_f32_e32 v15, v7, v6
	v_pk_mul_f32 v[6:7], v[8:9], v[8:9]
	s_nop 0
	v_add_f32_e32 v6, v6, v15
	v_add_f32_e32 v15, v7, v6
	v_pk_mul_f32 v[6:7], v[2:3], v[128:129] op_sel_hi:[1,0]
	s_nop 0
	v_pk_mul_f32 v[2:3], v[6:7], v[6:7]
	s_nop 0
	v_add_f32_e32 v2, v2, v15
	v_add_f32_e32 v15, v3, v2
	v_pk_mul_f32 v[2:3], v[4:5], v[128:129] op_sel_hi:[1,0]
	s_nop 0
	v_pk_mul_f32 v[4:5], v[2:3], v[2:3]
	s_nop 0
	v_add_f32_e32 v4, v4, v15
	v_add_f32_e32 v4, v5, v4
	v_mov_b32_e32 v5, v4
	s_nop 1
	v_permlane16_swap_b32_e32 v5, v4
	s_waitcnt lgkmcnt(0)
	v_add_f32_e32 v4, v4, v5
	v_mov_b32_e32 v5, v4
	s_nop 1
	v_permlane32_swap_b32_e32 v5, v4
	s_and_saveexec_b64 s[0:1], s[2:3]
	s_cbranch_execz .LBB0_981
	s_waitcnt lgkmcnt(0)
	v_add_f32_e32 v4, v4, v5
	ds_write_b32 v115, v4 offset:1216

; DI float lo2f(unsigned w) { return __uint_as_float(w << 16); }
; DI float hi2f(unsigned w) { return __uint_as_float(w & 0xffff0000u); }
; DI void st4(u16* p, float a, float b, float c, float d) { uint2 v; v.x = pack2(a, b); v.y = pack2(c, d); *reinterpret_cast<uint2*>(p) = v; }
; DI float red4(float v) { v += __shfl_xor(v, 16); v += __shfl_xor(v, 32); return v; }
; DI void prep_mla_tile(const Params& P, int l, int tt, char* lds, float* s_r, float* s_ss) {
;     ...
;       for (int j = 0; j < 4; ++j) {
;         const int tl = wb * 64 + 16 * j + jn, tok = tok0 + tl, pos = tok & (S - 1);
;         const float rkv = s_r[128 + tl];
;         const uint2 pl = ld4(proj + (size_t)tok * DINP + C_KPE + 4 * q);
;         const uint2 ph = ld4(proj + (size_t)tok * DINP + C_KPE + 16 + 4 * q);
;         const float kl[4] = {lo2f(pl.x), hi2f(pl.x), lo2f(pl.y), hi2f(pl.y)};
;         const float kh[4] = {lo2f(ph.x), hi2f(ph.x), lo2f(ph.y), hi2f(ph.y)};
;         float ss = 0.f;
; #pragma unroll
;         for (int i = 0; i < 4; ++i)
; #pragma unroll
;           for (int r = 0; r < 4; ++r) { const float v = acc[i][j][r] * rkv; acc[i][j][r] = v; ss += v * v; }
; #pragma unroll
;         for (int r = 0; r < 4; ++r) ss += kl[r] * kl[r] + kh[r] * kh[r];
;         ss = red4(ss);
;         const float rs = rsqrtf(ss * (1.0f / 96) + EPS);
; #pragma unroll
;         for (int i = 0; i < 4; ++i) {
;           const int d = 16 * i + 4 * q;
;           st4(mk + (size_t)tok * 576 + h * 96 + d, acc[i][j][0] * rs * gk[d], acc[i][j][1] * rs * gk[d + 1], acc[i][j][2] * rs * gk[d + 2], acc[i][j][3] * rs * gk[d + 3]);
;         }
;         float y1[4], y2[4];
; #pragma unroll
;         for (int r = 0; r < 4; ++r) {
;           const float2 cs = r32[pos * 16 + 4 * q + r];
;           const float x1 = kl[r] * rs * gk[64 + 4 * q + r], x2 = kh[r] * rs * gk[80 + 4 * q + r];
;           y1[r] = x1 * cs.x - x2 * cs.y; y2[r] = x2 * cs.x + x1 * cs.y;
;         }
;         st4(mk + (size_t)tok * 576 + h * 96 + 64 + 4 * q, y1[0], y1[1], y1[2], y1[3]);
;         st4(mk + (size_t)tok * 576 + h * 96 + 80 + 4 * q, y2[0], y2[1], y2[2], y2[3]);
.LBB0_1001:
	s_andn2_b64 vcc, exec, s[18:19]
	s_cbranch_vccnz .LBB0_998
	ds_read2_b32 v[128:129], v150 offset0:128 offset1:144
	global_load_dwordx2 v[134:135], v[108:109], off
	global_load_dwordx2 v[152:153], v[110:111], off
	s_mul_i32 s18, s17, 0x60
	s_ashr_i32 s19, s18, 31
	s_lshl_b64 s[18:19], s[18:19], 1
	s_waitcnt lgkmcnt(0)
	v_pk_mul_f32 v[156:157], v[64:65], v[128:129] op_sel_hi:[1,0]
	v_pk_mul_f32 v[162:163], v[62:63], v[128:129] op_sel_hi:[1,0]
	global_load_dwordx4 v[62:65], v[112:113], off
	v_pk_mul_f32 v[164:165], v[162:163], v[162:163]
	v_pk_mul_f32 v[158:159], v[156:157], v[156:157]
	v_pk_mul_f32 v[60:61], v[60:61], v[128:129] op_sel_hi:[1,0]
	v_pk_mul_f32 v[58:59], v[58:59], v[128:129] op_sel_hi:[1,0]
	v_pk_mul_f32 v[56:57], v[56:57], v[128:129] op_sel_hi:[1,0]
	v_pk_mul_f32 v[54:55], v[54:55], v[128:129] op_sel_hi:[1,0]
	v_pk_mul_f32 v[178:179], v[52:53], v[128:129] op_sel_hi:[1,0]
	v_pk_mul_f32 v[180:181], v[50:51], v[128:129] op_sel_hi:[1,0]
	v_add_f32_e32 v128, v164, v165
	v_add_f32_e32 v128, v158, v128
	v_pk_mul_f32 v[172:173], v[58:59], v[58:59]
	v_add_f32_e32 v128, v159, v128
	v_add_f32_e32 v128, v172, v128
	v_pk_mul_f32 v[168:169], v[60:61], v[60:61]
	v_add_f32_e32 v128, v173, v128
	v_add_f32_e32 v128, v168, v128
	v_pk_mul_f32 v[176:177], v[54:55], v[54:55]
	v_add_f32_e32 v128, v169, v128
	v_add_f32_e32 v128, v176, v128
	v_pk_mul_f32 v[174:175], v[56:57], v[56:57]
	v_add_f32_e32 v128, v177, v128
	v_add_f32_e32 v128, v174, v128
	v_pk_mul_f32 v[50:51], v[180:181], v[180:181]
	v_add_f32_e32 v128, v175, v128
	v_add_f32_e32 v50, v50, v128
	v_pk_mul_f32 v[52:53], v[178:179], v[178:179]
	v_add_f32_e32 v50, v51, v50
	v_add_f32_e32 v50, v52, v50
	v_add_f32_e32 v50, v53, v50
	s_add_u32 s18, s68, s18
	s_addc_u32 s19, s69, s19
	s_waitcnt vmcnt(2)
	v_lshlrev_b32_e32 v141, 16, v134
	s_waitcnt vmcnt(1)
	v_lshlrev_b32_e32 v143, 16, v152
	v_and_b32_e32 v142, 0xffff0000, v152
	v_and_b32_e32 v140, 0xffff0000, v134
	v_lshlrev_b32_e32 v137, 16, v135
	v_and_b32_e32 v136, 0xffff0000, v135
	v_pk_mul_f32 v[134:135], v[142:143], v[142:143]
	v_lshlrev_b32_e32 v139, 16, v153
	v_and_b32_e32 v138, 0xffff0000, v153
	v_pk_fma_f32 v[152:153], v[140:141], v[140:141], v[134:135]
	v_pk_mul_f32 v[134:135], v[138:139], v[138:139]
	v_add_f32_e32 v50, v153, v50
	v_pk_fma_f32 v[154:155], v[136:137], v[136:137], v[134:135]
	v_add_f32_e32 v50, v152, v50
	v_add_f32_e32 v50, v155, v50
	v_add_f32_e32 v50, v154, v50
	v_mov_b32_e32 v51, v50
	s_nop 1
	v_permlane16_swap_b32_e32 v51, v50
	v_lshl_add_u64 v[134:135], s[18:19], 0, v[72:73]
	v_lshl_add_u64 v[134:135], v[134:135], 0, v[0:1]
	s_waitcnt lgkmcnt(0)
	v_add_f32_e32 v50, v50, v51
	v_mov_b32_e32 v51, v50
	s_nop 1
	v_permlane32_swap_b32_e32 v51, v50
	s_waitcnt lgkmcnt(0)
	v_add_f32_e32 v50, v50, v51
	v_fmamk_f32 v50, v50, 0x3c2aaaab, v132
	v_cmp_gt_f32_e32 vcc, s37, v50
	v_mul_f32_e32 v51, 0x4b800000, v50
	s_nop 0
	v_cndmask_b32_e32 v50, v50, v51, vcc
	v_rsq_f32_e32 v50, v50
	s_nop 0
	v_mul_f32_e32 v51, 0x45800000, v50
	v_cndmask_b32_e32 v128, v50, v51, vcc
	v_pk_mul_f32 v[50:51], v[162:163], v[128:129] op_sel_hi:[1,0]
	v_pk_mul_f32 v[52:53], v[156:157], v[128:129] op_sel_hi:[1,0]
	s_waitcnt vmcnt(0)
	v_pk_mul_f32 v[50:51], v[62:63], v[50:51]
	v_pk_mul_f32 v[52:53], v[64:65], v[52:53]
	v_cvt_pk_bf16_f32 v50, v50, v51
	v_cvt_pk_bf16_f32 v51, v52, v53
	global_store_dwordx2 v[134:135], v[50:51], off
	global_load_dwordx4 v[50:53], v[112:113], off offset:64
	v_pk_mul_f32 v[58:59], v[58:59], v[128:129] op_sel_hi:[1,0]
	v_pk_mul_f32 v[54:55], v[54:55], v[128:129] op_sel_hi:[1,0]
	v_pk_mul_f32 v[62:63], v[128:129], v[142:143] op_sel_hi:[0,1]
	v_pk_mul_f32 v[140:141], v[128:129], v[140:141] op_sel_hi:[0,1]
	s_waitcnt vmcnt(0)
	v_pk_mul_f32 v[50:51], v[50:51], v[58:59]
	v_pk_mul_f32 v[58:59], v[60:61], v[128:129] op_sel_hi:[1,0]
	v_cvt_pk_bf16_f32 v50, v50, v51
	v_pk_mul_f32 v[52:53], v[52:53], v[58:59]
	s_nop 0
	v_cvt_pk_bf16_f32 v51, v52, v53
	global_store_dwordx2 v[134:135], v[50:51], off offset:32
	global_load_dwordx4 v[50:53], v[112:113], off offset:128
	s_waitcnt vmcnt(0)
	v_pk_mul_f32 v[50:51], v[50:51], v[54:55]
	v_pk_mul_f32 v[54:55], v[56:57], v[128:129] op_sel_hi:[1,0]
	v_cvt_pk_bf16_f32 v50, v50, v51
	v_pk_mul_f32 v[52:53], v[52:53], v[54:55]
	v_pk_mul_f32 v[54:55], v[180:181], v[128:129] op_sel_hi:[1,0]
	v_cvt_pk_bf16_f32 v51, v52, v53
	global_store_dwordx2 v[134:135], v[50:51], off offset:64
	global_load_dwordx4 v[50:53], v[112:113], off offset:192
	s_waitcnt vmcnt(0)
	v_pk_mul_f32 v[50:51], v[50:51], v[54:55]
	v_pk_mul_f32 v[54:55], v[178:179], v[128:129] op_sel_hi:[1,0]
	v_cvt_pk_bf16_f32 v50, v50, v51
	v_pk_mul_f32 v[52:53], v[52:53], v[54:55]
	s_nop 0
	v_cvt_pk_bf16_f32 v51, v52, v53
	global_store_dwordx2 v[134:135], v[50:51], off offset:96
	global_load_dwordx4 v[50:53], v[70:71], off offset:16
	s_nop 0
	global_load_dwordx4 v[54:57], v[70:71], off
	global_load_dwordx4 v[58:61], v[112:113], off offset:320
	s_waitcnt vmcnt(0)
	v_pk_mul_f32 v[58:59], v[62:63], v[58:59] op_sel:[1,0] op_sel_hi:[0,1]
	global_load_dwordx4 v[62:65], v[112:113], off offset:256
	s_waitcnt vmcnt(0)
; DI float lo2f(unsigned w) { return __uint_as_float(w << 16); }
; DI float hi2f(unsigned w) { return __uint_as_float(w & 0xffff0000u); }
; DI void st4(u16* p, float a, float b, float c, float d) { uint2 v; v.x = pack2(a, b); v.y = pack2(c, d); *reinterpret_cast<uint2*>(p) = v; }
; DI float red4(float v) { v += __shfl_xor(v, 16); v += __shfl_xor(v, 32); return v; }
; DI void prep_mla_tile(const Params& P, int l, int tt, char* lds, float* s_r, float* s_ss) {
;     ...
;       for (int j = 0; j < 4; ++j) {
;         const int tl = wb * 64 + 16 * j + jn, tok = tok0 + tl, pos = tok & (S - 1);
;         const float rkv = s_r[128 + tl];
;         const uint2 pl = ld4(proj + (size_t)tok * DINP + C_KPE + 4 * q);
;         const uint2 ph = ld4(proj + (size_t)tok * DINP + C_KPE + 16 + 4 * q);
;         const float kl[4] = {lo2f(pl.x), hi2f(pl.x), lo2f(pl.y), hi2f(pl.y)};
;         const float kh[4] = {lo2f(ph.x), hi2f(ph.x), lo2f(ph.y), hi2f(ph.y)};
;         float ss = 0.f;
; #pragma unroll
;         for (int i = 0; i < 4; ++i)
; #pragma unroll
;           for (int r = 0; r < 4; ++r) { const float v = acc[i][j][r] * rkv; acc[i][j][r] = v; ss += v * v; }
; #pragma unroll
;         for (int r = 0; r < 4; ++r) ss += kl[r] * kl[r] + kh[r] * kh[r];
;         ss = red4(ss);
;         const float rs = rsqrtf(ss * (1.0f / 96) + EPS);
; #pragma unroll
;         for (int i = 0; i < 4; ++i) {
;           const int d = 16 * i + 4 * q;
;           st4(mk + (size_t)tok * 576 + h * 96 + d, acc[i][j][0] * rs * gk[d], acc[i][j][1] * rs * gk[d + 1], acc[i][j][2] * rs * gk[d + 2], acc[i][j][3] * rs * gk[d + 3]);
;         }
;         float y1[4], y2[4];
; #pragma unroll
;         for (int r = 0; r < 4; ++r) {
;           const float2 cs = r32[pos * 16 + 4 * q + r];
;           const float x1 = kl[r] * rs * gk[64 + 4 * q + r], x2 = kh[r] * rs * gk[80 + 4 * q + r];
;           y1[r] = x1 * cs.x - x2 * cs.y; y2[r] = x2 * cs.x + x1 * cs.y;
;         }
;         st4(mk + (size_t)tok * 576 + h * 96 + 64 + 4 * q, y1[0], y1[1], y1[2], y1[3]);
;         st4(mk + (size_t)tok * 576 + h * 96 + 80 + 4 * q, y2[0], y2[1], y2[2], y2[3]);
	v_pk_mul_f32 v[62:63], v[140:141], v[62:63] op_sel:[1,0] op_sel_hi:[0,1]
	v_mov_b32_e32 v140, v54
	v_mov_b32_e32 v141, v56
	v_mov_b32_e32 v56, v55
	v_pk_mul_f32 v[54:55], v[56:57], v[58:59]
	v_pk_mul_f32 v[58:59], v[140:141], v[58:59]
	v_pk_fma_f32 v[54:55], v[140:141], v[62:63], v[54:55] neg_lo:[0,0,1] neg_hi:[0,0,1]
	v_pk_fma_f32 v[56:57], v[56:57], v[62:63], v[58:59]
	v_pk_mul_f32 v[58:59], v[128:129], v[138:139] op_sel_hi:[0,1]
	v_pk_mul_f32 v[58:59], v[58:59], v[60:61] op_sel:[1,0] op_sel_hi:[0,1]
	v_pk_mul_f32 v[60:61], v[128:129], v[136:137] op_sel_hi:[0,1]
	v_mov_b32_e32 v62, v50
	v_mov_b32_e32 v63, v52
	v_mov_b32_e32 v52, v51
	v_pk_mul_f32 v[60:61], v[60:61], v[64:65] op_sel:[1,0] op_sel_hi:[0,1]
	v_pk_mul_f32 v[50:51], v[52:53], v[58:59]
	v_pk_mul_f32 v[58:59], v[62:63], v[58:59]
	v_pk_fma_f32 v[50:51], v[62:63], v[60:61], v[50:51] neg_lo:[0,0,1] neg_hi:[0,0,1]
	v_pk_fma_f32 v[52:53], v[52:53], v[60:61], v[58:59]
	v_cvt_pk_bf16_f32 v54, v54, v55
	v_cvt_pk_bf16_f32 v55, v50, v51
	v_cvt_pk_bf16_f32 v50, v56, v57
	v_cvt_pk_bf16_f32 v51, v52, v53
	global_store_dwordx2 v[134:135], v[54:55], off offset:128
	global_store_dwordx2 v[134:135], v[50:51], off offset:160
	global_load_dwordx2 v[50:51], v[114:115], off
	s_nop 0
	global_load_dwordx2 v[58:59], v[116:117], off
	v_mov_b32_e32 v64, v129
	v_pk_mul_f32 v[128:129], v[48:49], v[64:65] op_sel_hi:[1,0]
	v_pk_mul_f32 v[136:137], v[46:47], v[64:65] op_sel_hi:[1,0]
	global_load_dwordx4 v[46:49], v[112:113], off
	v_pk_mul_f32 v[138:139], v[136:137], v[136:137]
	v_pk_mul_f32 v[134:135], v[128:129], v[128:129]
	v_add_f32_e32 v138, v138, v139
	v_pk_mul_f32 v[34:35], v[34:35], v[64:65] op_sel_hi:[1,0]
	v_add_f32_e32 v134, v134, v138
	v_pk_mul_f32 v[142:143], v[34:35], v[34:35]
	v_add_f32_e32 v134, v135, v134
	v_pk_mul_f32 v[140:141], v[36:37], v[64:65] op_sel_hi:[1,0]
	v_add_f32_e32 v134, v142, v134
	v_pk_mul_f32 v[36:37], v[140:141], v[140:141]
	v_add_f32_e32 v134, v143, v134
	v_pk_mul_f32 v[38:39], v[38:39], v[64:65] op_sel_hi:[1,0]
	v_add_f32_e32 v36, v36, v134
	v_pk_mul_f32 v[154:155], v[38:39], v[38:39]
	v_add_f32_e32 v36, v37, v36
	v_pk_mul_f32 v[40:41], v[40:41], v[64:65] op_sel_hi:[1,0]
	v_add_f32_e32 v36, v154, v36
	v_pk_mul_f32 v[152:153], v[40:41], v[40:41]
	v_add_f32_e32 v36, v155, v36
	v_pk_mul_f32 v[42:43], v[42:43], v[64:65] op_sel_hi:[1,0]
	v_add_f32_e32 v36, v152, v36
	v_pk_mul_f32 v[44:45], v[44:45], v[64:65] op_sel_hi:[1,0]
	v_pk_mul_f32 v[64:65], v[42:43], v[42:43]
	v_add_f32_e32 v36, v153, v36
	v_add_f32_e32 v36, v64, v36
	v_pk_mul_f32 v[156:157], v[44:45], v[44:45]
	v_add_f32_e32 v36, v65, v36
	v_add_f32_e32 v36, v156, v36
	v_add_f32_e32 v36, v157, v36
	s_waitcnt vmcnt(2)
	v_lshlrev_b32_e32 v57, 16, v50
	s_waitcnt vmcnt(1)
	v_lshlrev_b32_e32 v61, 16, v58
	v_and_b32_e32 v60, 0xffff0000, v58
	v_and_b32_e32 v56, 0xffff0000, v50
	v_lshlrev_b32_e32 v53, 16, v51
	v_and_b32_e32 v52, 0xffff0000, v51
	v_pk_mul_f32 v[50:51], v[60:61], v[60:61]
	v_lshlrev_b32_e32 v55, 16, v59
	v_and_b32_e32 v54, 0xffff0000, v59
	v_pk_fma_f32 v[58:59], v[56:57], v[56:57], v[50:51]
	v_pk_mul_f32 v[50:51], v[54:55], v[54:55]
	v_add_f32_e32 v36, v59, v36
	v_pk_fma_f32 v[62:63], v[52:53], v[52:53], v[50:51]
	v_add_f32_e32 v36, v58, v36
	v_add_f32_e32 v36, v63, v36
	v_add_f32_e32 v36, v62, v36
	v_mov_b32_e32 v37, v36
	s_nop 1
	v_permlane16_swap_b32_e32 v37, v36
	v_lshl_add_u64 v[50:51], s[18:19], 0, v[76:77]
	v_lshl_add_u64 v[50:51], v[50:51], 0, v[0:1]
	s_waitcnt lgkmcnt(0)
	v_add_f32_e32 v36, v36, v37
	v_mov_b32_e32 v37, v36
	s_nop 1
	v_permlane32_swap_b32_e32 v37, v36
	s_waitcnt lgkmcnt(0)
	v_add_f32_e32 v36, v36, v37
	v_fmamk_f32 v36, v36, 0x3c2aaaab, v132
	v_cmp_gt_f32_e32 vcc, s37, v36
	v_mul_f32_e32 v37, 0x4b800000, v36
	s_nop 0
	v_cndmask_b32_e32 v36, v36, v37, vcc
	v_rsq_f32_e32 v36, v36
	s_nop 0
	v_mul_f32_e32 v37, 0x45800000, v36
	v_cndmask_b32_e32 v58, v36, v37, vcc
	v_pk_mul_f32 v[36:37], v[136:137], v[58:59] op_sel_hi:[1,0]
	v_pk_mul_f32 v[38:39], v[38:39], v[58:59] op_sel_hi:[1,0]
	s_waitcnt vmcnt(0)
	v_pk_mul_f32 v[36:37], v[46:47], v[36:37]
	v_pk_mul_f32 v[46:47], v[128:129], v[58:59] op_sel_hi:[1,0]
	v_cvt_pk_bf16_f32 v36, v36, v37
	v_pk_mul_f32 v[46:47], v[48:49], v[46:47]
	v_pk_mul_f32 v[56:57], v[58:59], v[56:57] op_sel_hi:[0,1]
	v_cvt_pk_bf16_f32 v37, v46, v47
	global_store_dwordx2 v[50:51], v[36:37], off
	v_pk_mul_f32 v[46:47], v[34:35], v[58:59] op_sel_hi:[1,0]
	global_load_dwordx4 v[34:37], v[112:113], off offset:64
	s_waitcnt vmcnt(0)
	v_pk_mul_f32 v[34:35], v[34:35], v[46:47]
	v_pk_mul_f32 v[46:47], v[140:141], v[58:59] op_sel_hi:[1,0]
	v_cvt_pk_bf16_f32 v34, v34, v35
	v_pk_mul_f32 v[36:37], v[36:37], v[46:47]
	v_pk_mul_f32 v[46:47], v[58:59], v[60:61] op_sel_hi:[0,1]
	v_cvt_pk_bf16_f32 v35, v36, v37
	global_store_dwordx2 v[50:51], v[34:35], off offset:32
	global_load_dwordx4 v[34:37], v[112:113], off offset:128
	s_waitcnt vmcnt(0)
	v_pk_mul_f32 v[34:35], v[34:35], v[38:39]
	v_pk_mul_f32 v[38:39], v[40:41], v[58:59] op_sel_hi:[1,0]
	v_cvt_pk_bf16_f32 v34, v34, v35
	v_pk_mul_f32 v[36:37], v[36:37], v[38:39]
	v_pk_mul_f32 v[38:39], v[42:43], v[58:59] op_sel_hi:[1,0]
	v_cvt_pk_bf16_f32 v35, v36, v37
	global_store_dwordx2 v[50:51], v[34:35], off offset:64
	global_load_dwordx4 v[34:37], v[112:113], off offset:192
	s_waitcnt vmcnt(0)
	v_pk_mul_f32 v[34:35], v[34:35], v[38:39]
	v_pk_mul_f32 v[38:39], v[44:45], v[58:59] op_sel_hi:[1,0]
	v_cvt_pk_bf16_f32 v34, v34, v35
	v_pk_mul_f32 v[36:37], v[36:37], v[38:39]
	s_nop 0
	v_cvt_pk_bf16_f32 v35, v36, v37
	global_store_dwordx2 v[50:51], v[34:35], off offset:96
	global_load_dwordx4 v[34:37], v[74:75], off offset:16
	s_nop 0
	global_load_dwordx4 v[38:41], v[74:75], off
	global_load_dwordx4 v[42:45], v[112:113], off offset:320
	s_waitcnt vmcnt(0)
; DI float lo2f(unsigned w) { return __uint_as_float(w << 16); }
; DI float hi2f(unsigned w) { return __uint_as_float(w & 0xffff0000u); }
; DI void st4(u16* p, float a, float b, float c, float d) { uint2 v; v.x = pack2(a, b); v.y = pack2(c, d); *reinterpret_cast<uint2*>(p) = v; }
; DI float red4(float v) { v += __shfl_xor(v, 16); v += __shfl_xor(v, 32); return v; }
; DI void prep_mla_tile(const Params& P, int l, int tt, char* lds, float* s_r, float* s_ss) {
;     ...
;       for (int j = 0; j < 4; ++j) {
;         const int tl = wb * 64 + 16 * j + jn, tok = tok0 + tl, pos = tok & (S - 1);
;         const float rkv = s_r[128 + tl];
;         const uint2 pl = ld4(proj + (size_t)tok * DINP + C_KPE + 4 * q);
;         const uint2 ph = ld4(proj + (size_t)tok * DINP + C_KPE + 16 + 4 * q);
;         const float kl[4] = {lo2f(pl.x), hi2f(pl.x), lo2f(pl.y), hi2f(pl.y)};
;         const float kh[4] = {lo2f(ph.x), hi2f(ph.x), lo2f(ph.y), hi2f(ph.y)};
;         float ss = 0.f;
; #pragma unroll
;         for (int i = 0; i < 4; ++i)
; #pragma unroll
;           for (int r = 0; r < 4; ++r) { const float v = acc[i][j][r] * rkv; acc[i][j][r] = v; ss += v * v; }
; #pragma unroll
;         for (int r = 0; r < 4; ++r) ss += kl[r] * kl[r] + kh[r] * kh[r];
;         ss = red4(ss);
;         const float rs = rsqrtf(ss * (1.0f / 96) + EPS);
; #pragma unroll
;         for (int i = 0; i < 4; ++i) {
;           const int d = 16 * i + 4 * q;
;           st4(mk + (size_t)tok * 576 + h * 96 + d, acc[i][j][0] * rs * gk[d], acc[i][j][1] * rs * gk[d + 1], acc[i][j][2] * rs * gk[d + 2], acc[i][j][3] * rs * gk[d + 3]);
;         }
;         float y1[4], y2[4];
; #pragma unroll
;         for (int r = 0; r < 4; ++r) {
;           const float2 cs = r32[pos * 16 + 4 * q + r];
;           const float x1 = kl[r] * rs * gk[64 + 4 * q + r], x2 = kh[r] * rs * gk[80 + 4 * q + r];
;           y1[r] = x1 * cs.x - x2 * cs.y; y2[r] = x2 * cs.x + x1 * cs.y;
;         }
;         st4(mk + (size_t)tok * 576 + h * 96 + 64 + 4 * q, y1[0], y1[1], y1[2], y1[3]);
;         st4(mk + (size_t)tok * 576 + h * 96 + 80 + 4 * q, y2[0], y2[1], y2[2], y2[3]);
	v_pk_mul_f32 v[42:43], v[46:47], v[42:43] op_sel:[1,0] op_sel_hi:[0,1]
	global_load_dwordx4 v[46:49], v[112:113], off offset:256
	s_waitcnt vmcnt(0)
	v_pk_mul_f32 v[46:47], v[56:57], v[46:47] op_sel:[1,0] op_sel_hi:[0,1]
	v_mov_b32_e32 v56, v38
	v_mov_b32_e32 v57, v40
	v_mov_b32_e32 v40, v39
	v_pk_mul_f32 v[38:39], v[40:41], v[42:43]
	v_pk_mul_f32 v[42:43], v[56:57], v[42:43]
	v_pk_fma_f32 v[38:39], v[56:57], v[46:47], v[38:39] neg_lo:[0,0,1] neg_hi:[0,0,1]
	v_pk_fma_f32 v[40:41], v[40:41], v[46:47], v[42:43]
	v_pk_mul_f32 v[42:43], v[58:59], v[54:55] op_sel_hi:[0,1]
	v_pk_mul_f32 v[42:43], v[42:43], v[44:45] op_sel:[1,0] op_sel_hi:[0,1]
	v_pk_mul_f32 v[44:45], v[58:59], v[52:53] op_sel_hi:[0,1]
	v_mov_b32_e32 v46, v34
	v_mov_b32_e32 v47, v36
	v_mov_b32_e32 v36, v35
	v_pk_mul_f32 v[44:45], v[44:45], v[48:49] op_sel:[1,0] op_sel_hi:[0,1]
	v_pk_mul_f32 v[34:35], v[36:37], v[42:43]
	v_pk_mul_f32 v[42:43], v[46:47], v[42:43]
	v_pk_fma_f32 v[34:35], v[46:47], v[44:45], v[34:35] neg_lo:[0,0,1] neg_hi:[0,0,1]
	v_pk_fma_f32 v[36:37], v[36:37], v[44:45], v[42:43]
	v_cvt_pk_bf16_f32 v38, v38, v39
	v_cvt_pk_bf16_f32 v39, v34, v35
	v_cvt_pk_bf16_f32 v34, v40, v41
	v_cvt_pk_bf16_f32 v35, v36, v37
	global_store_dwordx2 v[50:51], v[38:39], off offset:128
	global_store_dwordx2 v[50:51], v[34:35], off offset:160
	ds_read2_b32 v[34:35], v150 offset0:160 offset1:176
	global_load_dwordx2 v[36:37], v[118:119], off
	global_load_dwordx2 v[46:47], v[120:121], off
	global_load_dwordx4 v[54:57], v[112:113], off
	s_waitcnt lgkmcnt(0)
	v_pk_mul_f32 v[30:31], v[30:31], v[34:35] op_sel_hi:[1,0]
	v_pk_mul_f32 v[32:33], v[32:33], v[34:35] op_sel_hi:[1,0]
	v_pk_mul_f32 v[52:53], v[30:31], v[30:31]
	v_pk_mul_f32 v[50:51], v[32:33], v[32:33]
	v_pk_mul_f32 v[28:29], v[28:29], v[34:35] op_sel_hi:[1,0]
	v_pk_mul_f32 v[26:27], v[26:27], v[34:35] op_sel_hi:[1,0]
	v_pk_mul_f32 v[24:25], v[24:25], v[34:35] op_sel_hi:[1,0]
	v_pk_mul_f32 v[22:23], v[22:23], v[34:35] op_sel_hi:[1,0]
	v_pk_mul_f32 v[128:129], v[20:21], v[34:35] op_sel_hi:[1,0]
	v_pk_mul_f32 v[134:135], v[18:19], v[34:35] op_sel_hi:[1,0]
	v_add_f32_e32 v34, v52, v53
	v_add_f32_e32 v34, v50, v34
	v_pk_mul_f32 v[60:61], v[26:27], v[26:27]
	v_add_f32_e32 v34, v51, v34
	v_add_f32_e32 v34, v60, v34
	v_pk_mul_f32 v[58:59], v[28:29], v[28:29]
	v_add_f32_e32 v34, v61, v34
	v_add_f32_e32 v34, v58, v34
	v_pk_mul_f32 v[64:65], v[22:23], v[22:23]
	v_add_f32_e32 v34, v59, v34
	v_add_f32_e32 v34, v64, v34
	v_pk_mul_f32 v[62:63], v[24:25], v[24:25]
	v_add_f32_e32 v34, v65, v34
	v_add_f32_e32 v34, v62, v34
	v_pk_mul_f32 v[18:19], v[134:135], v[134:135]
	v_add_f32_e32 v34, v63, v34
	v_add_f32_e32 v18, v18, v34
	v_pk_mul_f32 v[20:21], v[128:129], v[128:129]
	v_add_f32_e32 v18, v19, v18
	v_add_f32_e32 v18, v20, v18
	v_add_f32_e32 v18, v21, v18
	s_waitcnt vmcnt(2)
	v_lshlrev_b32_e32 v43, 16, v36
	s_waitcnt vmcnt(1)
	v_lshlrev_b32_e32 v45, 16, v46
	v_and_b32_e32 v44, 0xffff0000, v46
	v_and_b32_e32 v42, 0xffff0000, v36
	v_lshlrev_b32_e32 v39, 16, v37
	v_and_b32_e32 v38, 0xffff0000, v37
	v_pk_mul_f32 v[36:37], v[44:45], v[44:45]
	v_lshlrev_b32_e32 v41, 16, v47
	v_and_b32_e32 v40, 0xffff0000, v47
	v_pk_fma_f32 v[46:47], v[42:43], v[42:43], v[36:37]
	v_pk_mul_f32 v[36:37], v[40:41], v[40:41]
	v_add_f32_e32 v18, v47, v18
	v_pk_fma_f32 v[48:49], v[38:39], v[38:39], v[36:37]
	v_add_f32_e32 v18, v46, v18
	v_add_f32_e32 v18, v49, v18
	v_add_f32_e32 v18, v48, v18
	v_mov_b32_e32 v19, v18
	s_nop 1
	v_permlane16_swap_b32_e32 v19, v18
	v_lshl_add_u64 v[36:37], s[18:19], 0, v[80:81]
	v_lshl_add_u64 v[36:37], v[36:37], 0, v[0:1]
	s_waitcnt lgkmcnt(0)
	v_add_f32_e32 v18, v18, v19
	v_mov_b32_e32 v19, v18
	s_nop 1
	v_permlane32_swap_b32_e32 v19, v18
	s_waitcnt lgkmcnt(0)
	v_add_f32_e32 v18, v18, v19
	v_fmamk_f32 v18, v18, 0x3c2aaaab, v132
	v_cmp_gt_f32_e32 vcc, s37, v18
	v_mul_f32_e32 v19, 0x4b800000, v18
	s_nop 0
	v_cndmask_b32_e32 v18, v18, v19, vcc
	v_rsq_f32_e32 v18, v18
	s_nop 0
	v_mul_f32_e32 v19, 0x45800000, v18
	v_cndmask_b32_e32 v34, v18, v19, vcc
	v_pk_mul_f32 v[18:19], v[30:31], v[34:35] op_sel_hi:[1,0]
	v_pk_mul_f32 v[20:21], v[32:33], v[34:35] op_sel_hi:[1,0]
	s_waitcnt vmcnt(0)
	v_pk_mul_f32 v[18:19], v[54:55], v[18:19]
	v_pk_mul_f32 v[20:21], v[56:57], v[20:21]
	v_cvt_pk_bf16_f32 v18, v18, v19
	v_cvt_pk_bf16_f32 v19, v20, v21
	global_store_dwordx2 v[36:37], v[18:19], off
	global_load_dwordx4 v[18:21], v[112:113], off offset:64
	v_pk_mul_f32 v[26:27], v[26:27], v[34:35] op_sel_hi:[1,0]
	v_pk_mul_f32 v[22:23], v[22:23], v[34:35] op_sel_hi:[1,0]
	v_pk_mul_f32 v[30:31], v[34:35], v[44:45] op_sel_hi:[0,1]
	v_pk_mul_f32 v[42:43], v[34:35], v[42:43] op_sel_hi:[0,1]
	s_waitcnt vmcnt(0)
	v_pk_mul_f32 v[18:19], v[18:19], v[26:27]
	v_pk_mul_f32 v[26:27], v[28:29], v[34:35] op_sel_hi:[1,0]
	v_cvt_pk_bf16_f32 v18, v18, v19
	v_pk_mul_f32 v[20:21], v[20:21], v[26:27]
	s_nop 0
	v_cvt_pk_bf16_f32 v19, v20, v21
	global_store_dwordx2 v[36:37], v[18:19], off offset:32
	global_load_dwordx4 v[18:21], v[112:113], off offset:128
	s_waitcnt vmcnt(0)
	v_pk_mul_f32 v[18:19], v[18:19], v[22:23]
	v_pk_mul_f32 v[22:23], v[24:25], v[34:35] op_sel_hi:[1,0]
	v_cvt_pk_bf16_f32 v18, v18, v19
	v_pk_mul_f32 v[20:21], v[20:21], v[22:23]
	v_pk_mul_f32 v[22:23], v[134:135], v[34:35] op_sel_hi:[1,0]
	v_cvt_pk_bf16_f32 v19, v20, v21
	global_store_dwordx2 v[36:37], v[18:19], off offset:64
	global_load_dwordx4 v[18:21], v[112:113], off offset:192
	s_waitcnt vmcnt(0)
; DI float lo2f(unsigned w) { return __uint_as_float(w << 16); }
; DI float hi2f(unsigned w) { return __uint_as_float(w & 0xffff0000u); }
; DI void st4(u16* p, float a, float b, float c, float d) { uint2 v; v.x = pack2(a, b); v.y = pack2(c, d); *reinterpret_cast<uint2*>(p) = v; }
; DI float red4(float v) { v += __shfl_xor(v, 16); v += __shfl_xor(v, 32); return v; }
; DI void prep_mla_tile(const Params& P, int l, int tt, char* lds, float* s_r, float* s_ss) {
;     ...
;       for (int j = 0; j < 4; ++j) {
;         const int tl = wb * 64 + 16 * j + jn, tok = tok0 + tl, pos = tok & (S - 1);
;         const float rkv = s_r[128 + tl];
;         const uint2 pl = ld4(proj + (size_t)tok * DINP + C_KPE + 4 * q);
;         const uint2 ph = ld4(proj + (size_t)tok * DINP + C_KPE + 16 + 4 * q);
;         const float kl[4] = {lo2f(pl.x), hi2f(pl.x), lo2f(pl.y), hi2f(pl.y)};
;         const float kh[4] = {lo2f(ph.x), hi2f(ph.x), lo2f(ph.y), hi2f(ph.y)};
;         float ss = 0.f;
; #pragma unroll
;         for (int i = 0; i < 4; ++i)
; #pragma unroll
;           for (int r = 0; r < 4; ++r) { const float v = acc[i][j][r] * rkv; acc[i][j][r] = v; ss += v * v; }
; #pragma unroll
;         for (int r = 0; r < 4; ++r) ss += kl[r] * kl[r] + kh[r] * kh[r];
;         ss = red4(ss);
;         const float rs = rsqrtf(ss * (1.0f / 96) + EPS);
; #pragma unroll
;         for (int i = 0; i < 4; ++i) {
;           const int d = 16 * i + 4 * q;
;           st4(mk + (size_t)tok * 576 + h * 96 + d, acc[i][j][0] * rs * gk[d], acc[i][j][1] * rs * gk[d + 1], acc[i][j][2] * rs * gk[d + 2], acc[i][j][3] * rs * gk[d + 3]);
;         }
;         float y1[4], y2[4];
; #pragma unroll
;         for (int r = 0; r < 4; ++r) {
;           const float2 cs = r32[pos * 16 + 4 * q + r];
;           const float x1 = kl[r] * rs * gk[64 + 4 * q + r], x2 = kh[r] * rs * gk[80 + 4 * q + r];
;           y1[r] = x1 * cs.x - x2 * cs.y; y2[r] = x2 * cs.x + x1 * cs.y;
;         }
;         st4(mk + (size_t)tok * 576 + h * 96 + 64 + 4 * q, y1[0], y1[1], y1[2], y1[3]);
;         st4(mk + (size_t)tok * 576 + h * 96 + 80 + 4 * q, y2[0], y2[1], y2[2], y2[3]);
	v_pk_mul_f32 v[18:19], v[18:19], v[22:23]
	v_pk_mul_f32 v[22:23], v[128:129], v[34:35] op_sel_hi:[1,0]
	v_cvt_pk_bf16_f32 v18, v18, v19
	v_pk_mul_f32 v[20:21], v[20:21], v[22:23]
	s_nop 0
	v_cvt_pk_bf16_f32 v19, v20, v21
	global_store_dwordx2 v[36:37], v[18:19], off offset:96
	global_load_dwordx4 v[18:21], v[78:79], off offset:16
	s_nop 0
	global_load_dwordx4 v[22:25], v[78:79], off
	global_load_dwordx4 v[26:29], v[112:113], off offset:320
	s_waitcnt vmcnt(0)
	v_pk_mul_f32 v[26:27], v[30:31], v[26:27] op_sel:[1,0] op_sel_hi:[0,1]
	global_load_dwordx4 v[30:33], v[112:113], off offset:256
	s_waitcnt vmcnt(0)
	v_pk_mul_f32 v[30:31], v[42:43], v[30:31] op_sel:[1,0] op_sel_hi:[0,1]
	v_mov_b32_e32 v42, v22
	v_mov_b32_e32 v43, v24
	v_mov_b32_e32 v24, v23
	v_pk_mul_f32 v[22:23], v[24:25], v[26:27]
	v_pk_mul_f32 v[26:27], v[42:43], v[26:27]
	v_pk_fma_f32 v[22:23], v[42:43], v[30:31], v[22:23] neg_lo:[0,0,1] neg_hi:[0,0,1]
	v_pk_fma_f32 v[24:25], v[24:25], v[30:31], v[26:27]
	v_pk_mul_f32 v[26:27], v[34:35], v[40:41] op_sel_hi:[0,1]
	v_pk_mul_f32 v[26:27], v[26:27], v[28:29] op_sel:[1,0] op_sel_hi:[0,1]
	v_pk_mul_f32 v[28:29], v[34:35], v[38:39] op_sel_hi:[0,1]
	v_mov_b32_e32 v30, v18
	v_mov_b32_e32 v31, v20
	v_mov_b32_e32 v20, v19
	v_pk_mul_f32 v[28:29], v[28:29], v[32:33] op_sel:[1,0] op_sel_hi:[0,1]
	v_pk_mul_f32 v[18:19], v[20:21], v[26:27]
	v_pk_mul_f32 v[26:27], v[30:31], v[26:27]
	v_pk_fma_f32 v[18:19], v[30:31], v[28:29], v[18:19] neg_lo:[0,0,1] neg_hi:[0,0,1]
	v_pk_fma_f32 v[20:21], v[20:21], v[28:29], v[26:27]
	v_cvt_pk_bf16_f32 v22, v22, v23
	v_cvt_pk_bf16_f32 v23, v18, v19
	v_cvt_pk_bf16_f32 v18, v24, v25
	v_cvt_pk_bf16_f32 v19, v20, v21
	global_store_dwordx2 v[36:37], v[22:23], off offset:128
	global_store_dwordx2 v[36:37], v[18:19], off offset:160
	global_load_dwordx2 v[24:25], v[122:123], off
	global_load_dwordx2 v[32:33], v[124:125], off
	s_waitcnt vmcnt(1)
	v_lshlrev_b32_e32 v27, 16, v24
	v_and_b32_e32 v26, 0xffff0000, v24
	s_waitcnt vmcnt(0)
	v_and_b32_e32 v24, 0xffff0000, v33
	v_lshlrev_b32_e32 v21, 16, v25
	v_lshlrev_b32_e32 v23, 16, v33
	v_and_b32_e32 v25, 0xffff0000, v25
	v_mov_b32_e32 v22, v24
	v_lshlrev_b32_e32 v29, 16, v32
	v_and_b32_e32 v28, 0xffff0000, v32
	v_mov_b32_e32 v20, v25
	v_pk_mul_f32 v[32:33], v[22:23], v[22:23]
	v_pk_mul_f32 v[18:19], v[28:29], v[28:29]
	v_pk_fma_f32 v[32:33], v[20:21], v[20:21], v[32:33]
	v_mov_b32_e32 v20, v35
	global_load_dwordx4 v[34:37], v[112:113], off
	v_pk_mul_f32 v[14:15], v[14:15], v[20:21] op_sel_hi:[1,0]
	v_pk_mul_f32 v[16:17], v[16:17], v[20:21] op_sel_hi:[1,0]
	v_pk_mul_f32 v[40:41], v[14:15], v[14:15]
	v_pk_mul_f32 v[38:39], v[16:17], v[16:17]
	v_pk_mul_f32 v[12:13], v[12:13], v[20:21] op_sel_hi:[1,0]
	v_pk_mul_f32 v[10:11], v[10:11], v[20:21] op_sel_hi:[1,0]
	v_pk_mul_f32 v[8:9], v[8:9], v[20:21] op_sel_hi:[1,0]
	v_pk_mul_f32 v[6:7], v[6:7], v[20:21] op_sel_hi:[1,0]
	v_pk_mul_f32 v[50:51], v[4:5], v[20:21] op_sel_hi:[1,0]
	v_pk_mul_f32 v[52:53], v[2:3], v[20:21] op_sel_hi:[1,0]
	v_add_f32_e32 v20, v40, v41
	v_add_f32_e32 v20, v38, v20
	v_pk_mul_f32 v[44:45], v[10:11], v[10:11]
	v_add_f32_e32 v20, v39, v20
	v_add_f32_e32 v20, v44, v20
	v_pk_mul_f32 v[42:43], v[12:13], v[12:13]
	v_add_f32_e32 v20, v45, v20
	v_add_f32_e32 v20, v42, v20
	v_pk_mul_f32 v[48:49], v[6:7], v[6:7]
	v_add_f32_e32 v20, v43, v20
	v_add_f32_e32 v20, v48, v20
	v_pk_mul_f32 v[46:47], v[8:9], v[8:9]
	v_add_f32_e32 v20, v49, v20
	v_add_f32_e32 v20, v46, v20
	v_pk_mul_f32 v[2:3], v[52:53], v[52:53]
	v_add_f32_e32 v20, v47, v20
	v_add_f32_e32 v2, v2, v20
	v_pk_mul_f32 v[4:5], v[50:51], v[50:51]
	v_add_f32_e32 v2, v3, v2
	v_add_f32_e32 v2, v4, v2
	v_pk_fma_f32 v[30:31], v[26:27], v[26:27], v[18:19]
	v_add_f32_e32 v2, v5, v2
	v_add_f32_e32 v2, v31, v2
	v_add_f32_e32 v2, v30, v2
	v_add_f32_e32 v2, v33, v2
	v_add_f32_e32 v2, v32, v2
	v_mov_b32_e32 v3, v2
	s_nop 1
	v_permlane16_swap_b32_e32 v3, v2
	v_lshl_add_u64 v[18:19], s[18:19], 0, v[84:85]
	v_lshl_add_u64 v[18:19], v[18:19], 0, v[0:1]
	s_mov_b64 s[18:19], 0xa0
	v_lshl_add_u64 v[134:135], v[18:19], 0, s[18:19]
	s_waitcnt lgkmcnt(0)
; DI float lo2f(unsigned w) { return __uint_as_float(w << 16); }
; DI float hi2f(unsigned w) { return __uint_as_float(w & 0xffff0000u); }
; DI void st4(u16* p, float a, float b, float c, float d) { uint2 v; v.x = pack2(a, b); v.y = pack2(c, d); *reinterpret_cast<uint2*>(p) = v; }
; DI float red4(float v) { v += __shfl_xor(v, 16); v += __shfl_xor(v, 32); return v; }
; DI void prep_mla_tile(const Params& P, int l, int tt, char* lds, float* s_r, float* s_ss) {
;     ...
;       for (int j = 0; j < 4; ++j) {
;         const int tl = wb * 64 + 16 * j + jn, tok = tok0 + tl, pos = tok & (S - 1);
;         const float rkv = s_r[128 + tl];
;         const uint2 pl = ld4(proj + (size_t)tok * DINP + C_KPE + 4 * q);
;         const uint2 ph = ld4(proj + (size_t)tok * DINP + C_KPE + 16 + 4 * q);
;         const float kl[4] = {lo2f(pl.x), hi2f(pl.x), lo2f(pl.y), hi2f(pl.y)};
;         const float kh[4] = {lo2f(ph.x), hi2f(ph.x), lo2f(ph.y), hi2f(ph.y)};
;         float ss = 0.f;
; #pragma unroll
;         for (int i = 0; i < 4; ++i)
; #pragma unroll
;           for (int r = 0; r < 4; ++r) { const float v = acc[i][j][r] * rkv; acc[i][j][r] = v; ss += v * v; }
; #pragma unroll
;         for (int r = 0; r < 4; ++r) ss += kl[r] * kl[r] + kh[r] * kh[r];
;         ss = red4(ss);
;         const float rs = rsqrtf(ss * (1.0f / 96) + EPS);
; #pragma unroll
;         for (int i = 0; i < 4; ++i) {
;           const int d = 16 * i + 4 * q;
;           st4(mk + (size_t)tok * 576 + h * 96 + d, acc[i][j][0] * rs * gk[d], acc[i][j][1] * rs * gk[d + 1], acc[i][j][2] * rs * gk[d + 2], acc[i][j][3] * rs * gk[d + 3]);
;         }
;         float y1[4], y2[4];
; #pragma unroll
;         for (int r = 0; r < 4; ++r) {
;           const float2 cs = r32[pos * 16 + 4 * q + r];
;           const float x1 = kl[r] * rs * gk[64 + 4 * q + r], x2 = kh[r] * rs * gk[80 + 4 * q + r];
;           y1[r] = x1 * cs.x - x2 * cs.y; y2[r] = x2 * cs.x + x1 * cs.y;
;         }
;         st4(mk + (size_t)tok * 576 + h * 96 + 64 + 4 * q, y1[0], y1[1], y1[2], y1[3]);
;         st4(mk + (size_t)tok * 576 + h * 96 + 80 + 4 * q, y2[0], y2[1], y2[2], y2[3]);
	v_add_f32_e32 v2, v2, v3
	v_mov_b32_e32 v3, v2
	s_nop 1
	v_permlane32_swap_b32_e32 v3, v2
	s_waitcnt lgkmcnt(0)
	v_add_f32_e32 v2, v2, v3
	v_fmamk_f32 v2, v2, 0x3c2aaaab, v132
	v_cmp_gt_f32_e32 vcc, s37, v2
	v_mul_f32_e32 v3, 0x4b800000, v2
	s_nop 0
	v_cndmask_b32_e32 v2, v2, v3, vcc
	v_rsq_f32_e32 v2, v2
	s_nop 0
	v_mul_f32_e32 v3, 0x45800000, v2
	v_cndmask_b32_e32 v20, v2, v3, vcc
	v_pk_mul_f32 v[2:3], v[14:15], v[20:21] op_sel_hi:[1,0]
	v_pk_mul_f32 v[4:5], v[16:17], v[20:21] op_sel_hi:[1,0]
	v_pk_mul_f32 v[10:11], v[10:11], v[20:21] op_sel_hi:[1,0]
	v_pk_mul_f32 v[6:7], v[6:7], v[20:21] op_sel_hi:[1,0]
	v_pk_mul_f32 v[14:15], v[20:21], v[28:29] op_sel_hi:[0,1]
	v_pk_mul_f32 v[26:27], v[20:21], v[26:27] op_sel_hi:[0,1]
	s_waitcnt vmcnt(0)
	v_pk_mul_f32 v[2:3], v[34:35], v[2:3]
	v_pk_mul_f32 v[4:5], v[36:37], v[4:5]
	v_cvt_pk_bf16_f32 v2, v2, v3
	v_cvt_pk_bf16_f32 v3, v4, v5
	global_store_dwordx2 v[18:19], v[2:3], off
	global_load_dwordx4 v[2:5], v[112:113], off offset:64
	s_waitcnt vmcnt(0)
	v_pk_mul_f32 v[2:3], v[2:3], v[10:11]
	v_pk_mul_f32 v[10:11], v[12:13], v[20:21] op_sel_hi:[1,0]
	v_cvt_pk_bf16_f32 v2, v2, v3
	v_pk_mul_f32 v[4:5], v[4:5], v[10:11]
	s_nop 0
	v_cvt_pk_bf16_f32 v3, v4, v5
	global_store_dwordx2 v[18:19], v[2:3], off offset:32
	global_load_dwordx4 v[2:5], v[112:113], off offset:128
	s_waitcnt vmcnt(0)
	v_pk_mul_f32 v[2:3], v[2:3], v[6:7]
	v_pk_mul_f32 v[6:7], v[8:9], v[20:21] op_sel_hi:[1,0]
	v_cvt_pk_bf16_f32 v2, v2, v3
	v_pk_mul_f32 v[4:5], v[4:5], v[6:7]
	v_pk_mul_f32 v[6:7], v[52:53], v[20:21] op_sel_hi:[1,0]
	v_cvt_pk_bf16_f32 v3, v4, v5
	global_store_dwordx2 v[18:19], v[2:3], off offset:64
	global_load_dwordx4 v[2:5], v[112:113], off offset:192
	s_waitcnt vmcnt(0)
	v_pk_mul_f32 v[2:3], v[2:3], v[6:7]
	v_pk_mul_f32 v[6:7], v[50:51], v[20:21] op_sel_hi:[1,0]
	v_cvt_pk_bf16_f32 v2, v2, v3
	v_pk_mul_f32 v[4:5], v[4:5], v[6:7]
	s_nop 0
	v_cvt_pk_bf16_f32 v3, v4, v5
	global_store_dwordx2 v[18:19], v[2:3], off offset:96
	global_load_dwordx4 v[2:5], v[82:83], off
	s_nop 0
	global_load_dwordx4 v[6:9], v[82:83], off offset:16
	global_load_dwordx4 v[10:13], v[112:113], off offset:320
	s_waitcnt vmcnt(1)
	v_mov_b32_e32 v22, v6
	s_waitcnt vmcnt(0)
	v_pk_mul_f32 v[10:11], v[14:15], v[10:11] op_sel:[1,0] op_sel_hi:[0,1]
	global_load_dwordx4 v[14:17], v[112:113], off offset:256
	s_waitcnt vmcnt(0)
	v_pk_mul_f32 v[14:15], v[26:27], v[14:15] op_sel:[1,0] op_sel_hi:[0,1]
	v_mov_b32_e32 v26, v2
	v_mov_b32_e32 v27, v4
	v_mov_b32_e32 v4, v3
	v_pk_mul_f32 v[2:3], v[4:5], v[10:11]
	v_pk_mul_f32 v[10:11], v[26:27], v[10:11]
	v_pk_fma_f32 v[2:3], v[26:27], v[14:15], v[2:3] neg_lo:[0,0,1] neg_hi:[0,0,1]
	v_pk_fma_f32 v[4:5], v[4:5], v[14:15], v[10:11]
	v_mul_f32_e32 v10, v20, v21
	v_mul_f32_e32 v10, v10, v16
	v_mul_f32_e32 v11, v20, v23
	v_pk_mul_f32 v[14:15], v[20:21], v[24:25] op_sel_hi:[0,1]
	v_mov_b32_e32 v16, v13
	v_mul_f32_e32 v12, v11, v12
	v_pk_mul_f32 v[14:15], v[14:15], v[16:17]
	v_mul_f32_e32 v16, v6, v12
	v_mul_f32_e32 v20, v7, v10
	v_mov_b32_e32 v6, v7
	v_mov_b32_e32 v7, v9
	v_mov_b32_e32 v13, v14
	v_mov_b32_e32 v23, v8
	v_mov_b32_e32 v11, v15
	v_pk_mul_f32 v[6:7], v[6:7], v[12:13]
	v_pk_mul_f32 v[8:9], v[8:9], v[14:15]
	v_pk_fma_f32 v[6:7], v[22:23], v[10:11], v[6:7] neg_lo:[0,0,1] neg_hi:[0,0,1]
	v_mov_b32_e32 v21, v9
	v_mov_b32_e32 v17, v8
	v_cvt_pk_bf16_f32 v2, v2, v3
	v_cvt_pk_bf16_f32 v3, v6, v7
	v_pk_add_f32 v[128:129], v[20:21], v[16:17]
	global_store_dwordx2 v[18:19], v[2:3], off offset:128
	v_cvt_pk_bf16_f32 v2, v4, v5
	global_store_dword v[18:19], v2, off offset:160
	s_branch .LBB0_998
